# wave 1's seam invalidate no longer waited for at the seam: the later hook (GEMM preamble / norm body) waits for it before its barrier
# speedup vs baseline: 1.0252x; 1.0012x over previous
.Lnw_skip_n0g:
	s_or_b64 exec, exec, s[40:41]
	s_waitcnt vmcnt(36)
	s_barrier
	global_load_dwordx2 v[86:87], v1, s[58:59] offset:0
	global_load_dwordx2 v[90:91], v1, s[58:59] offset:512
	global_load_dwordx2 v[94:95], v1, s[58:59] offset:1024
	global_load_dwordx2 v[98:99], v1, s[58:59] offset:1536
	global_load_dwordx2 v[88:89], v1, s[60:61] offset:0
	global_load_dwordx2 v[92:93], v1, s[60:61] offset:512
	global_load_dwordx2 v[96:97], v1, s[60:61] offset:1024
	global_load_dwordx2 v[100:101], v1, s[60:61] offset:1536
	s_add_u32 s58, s58, 0x800
	s_addc_u32 s59, s59, 0
	s_add_u32 s60, s60, 0x800
	s_addc_u32 s61, s61, 0
	global_load_dwordx2 v[118:119], v1, s[58:59] offset:0
	global_load_dwordx2 v[122:123], v1, s[58:59] offset:512
	global_load_dwordx2 v[134:135], v1, s[58:59] offset:1024
	global_load_dwordx2 v[138:139], v1, s[58:59] offset:1536
	global_load_dwordx2 v[120:121], v1, s[60:61] offset:0
	global_load_dwordx2 v[124:125], v1, s[60:61] offset:512
	global_load_dwordx2 v[136:137], v1, s[60:61] offset:1024
	global_load_dwordx2 v[140:141], v1, s[60:61] offset:1536
	s_add_u32 s58, s58, 0x800
	s_addc_u32 s59, s59, 0
	s_add_u32 s60, s60, 0x800
	s_addc_u32 s61, s61, 0
	global_load_dwordx2 v[172:173], v1, s[58:59] offset:0
	global_load_dwordx2 v[176:177], v1, s[58:59] offset:512
	global_load_dwordx2 v[204:205], v1, s[58:59] offset:1024
	global_load_dwordx2 v[214:215], v1, s[58:59] offset:1536
	global_load_dwordx2 v[174:175], v1, s[60:61] offset:0
	global_load_dwordx2 v[178:179], v1, s[60:61] offset:512
	global_load_dwordx2 v[206:207], v1, s[60:61] offset:1024
	global_load_dwordx2 v[216:217], v1, s[60:61] offset:1536
	s_add_u32 s58, s58, 0x800
	s_addc_u32 s59, s59, 0
	s_add_u32 s60, s60, 0x800
	s_addc_u32 s61, s61, 0
	global_load_dwordx2 v[234:235], v1, s[58:59] offset:0
	global_load_dwordx2 v[238:239], v1, s[58:59] offset:512
	global_load_dwordx2 v[242:243], v1, s[58:59] offset:1024
	global_load_dwordx2 v[246:247], v1, s[58:59] offset:1536
	global_load_dwordx2 v[236:237], v1, s[60:61] offset:0
	global_load_dwordx2 v[240:241], v1, s[60:61] offset:512
	global_load_dwordx2 v[244:245], v1, s[60:61] offset:1024
	global_load_dwordx2 v[248:249], v1, s[60:61] offset:1536
	s_add_u32 s58, s58, 0x800
	s_addc_u32 s59, s59, 0
	s_add_u32 s60, s60, 0x800
	s_addc_u32 s61, s61, 0
	s_waitcnt vmcnt(24)
	v_lshlrev_b32_e32 v14, 16, v86
	v_and_b32_e32 v15, 0xffff0000, v86
	v_lshlrev_b32_e32 v16, 16, v88
	v_and_b32_e32 v17, 0xffff0000, v88
	v_lshlrev_b32_e32 v18, 16, v87
	v_and_b32_e32 v19, 0xffff0000, v87
	v_lshlrev_b32_e32 v20, 16, v89
	v_and_b32_e32 v21, 0xffff0000, v89
	v_pk_add_f32 v[86:87], v[14:15], v[16:17]
	v_pk_add_f32 v[88:89], v[18:19], v[20:21]
	v_lshlrev_b32_e32 v14, 16, v90
	v_and_b32_e32 v15, 0xffff0000, v90
	v_lshlrev_b32_e32 v16, 16, v92
	v_and_b32_e32 v17, 0xffff0000, v92
	v_lshlrev_b32_e32 v18, 16, v91
	v_and_b32_e32 v19, 0xffff0000, v91
	v_lshlrev_b32_e32 v20, 16, v93
	v_and_b32_e32 v21, 0xffff0000, v93
	v_pk_add_f32 v[90:91], v[14:15], v[16:17]
	v_pk_add_f32 v[92:93], v[18:19], v[20:21]
	v_lshlrev_b32_e32 v14, 16, v94
	v_and_b32_e32 v15, 0xffff0000, v94
	v_lshlrev_b32_e32 v16, 16, v96
	v_and_b32_e32 v17, 0xffff0000, v96
	v_lshlrev_b32_e32 v18, 16, v95
	v_and_b32_e32 v19, 0xffff0000, v95
	v_lshlrev_b32_e32 v20, 16, v97
	v_and_b32_e32 v21, 0xffff0000, v97
	v_pk_add_f32 v[94:95], v[14:15], v[16:17]
	v_pk_add_f32 v[96:97], v[18:19], v[20:21]
	v_lshlrev_b32_e32 v14, 16, v98
	v_and_b32_e32 v15, 0xffff0000, v98
	v_lshlrev_b32_e32 v16, 16, v100
	v_and_b32_e32 v17, 0xffff0000, v100
	v_lshlrev_b32_e32 v18, 16, v99
	v_and_b32_e32 v19, 0xffff0000, v99
	v_lshlrev_b32_e32 v20, 16, v101
	v_and_b32_e32 v21, 0xffff0000, v101
	v_pk_add_f32 v[98:99], v[14:15], v[16:17]
	v_pk_add_f32 v[100:101], v[18:19], v[20:21]
	v_pk_mul_f32 v[12:13], v[86:87], v[86:87]
	v_pk_fma_f32 v[12:13], v[88:89], v[88:89], v[12:13]
	v_pk_fma_f32 v[12:13], v[90:91], v[90:91], v[12:13]
	v_pk_fma_f32 v[12:13], v[92:93], v[92:93], v[12:13]
	v_pk_fma_f32 v[12:13], v[94:95], v[94:95], v[12:13]
	v_pk_fma_f32 v[12:13], v[96:97], v[96:97], v[12:13]
	v_pk_fma_f32 v[12:13], v[98:99], v[98:99], v[12:13]
	v_pk_fma_f32 v[12:13], v[100:101], v[100:101], v[12:13]
	v_add_f32_e32 v5, v12, v13
	s_nop 1
	v_add_f32_dpp v5, v5, v5 quad_perm:[1,0,3,2] row_mask:0xf bank_mask:0xf
	s_nop 1
	v_add_f32_dpp v5, v5, v5 quad_perm:[2,3,0,1] row_mask:0xf bank_mask:0xf
	s_nop 1
	v_add_f32_dpp v5, v5, v5 row_half_mirror row_mask:0xf bank_mask:0xf
	s_nop 1
	v_add_f32_dpp v5, v5, v5 row_mirror row_mask:0xf bank_mask:0xf
	s_nop 1
	v_add_f32_dpp v5, v5, v5 row_bcast:15 row_mask:0xa bank_mask:0xf
	s_nop 1
	v_add_f32_dpp v5, v5, v5 row_bcast:31 row_mask:0xc bank_mask:0xf
	s_nop 1
	v_readlane_b32 s32, v5, 63
	s_nop 1
	v_mov_b32_e32 v6, s32
	v_fmamk_f32 v6, v6, 0x3a800000, v146
	v_rsq_f32_e32 v6, v6
	s_nop 0
	v_mul_f32_e32 v8, 0.5, v6
	v_pk_mul_f32 v[14:15], v[86:87], v[8:9] op_sel_hi:[1,0]
	v_pk_fma_f32 v[70:71], v[22:23], v[14:15], v[70:71]
	v_pk_mul_f32 v[14:15], v[88:89], v[8:9] op_sel_hi:[1,0]
	v_pk_fma_f32 v[72:73], v[24:25], v[14:15], v[72:73]
	v_pk_mul_f32 v[14:15], v[90:91], v[8:9] op_sel_hi:[1,0]
	v_pk_fma_f32 v[74:75], v[26:27], v[14:15], v[74:75]
	v_pk_mul_f32 v[14:15], v[92:93], v[8:9] op_sel_hi:[1,0]
	v_pk_fma_f32 v[76:77], v[28:29], v[14:15], v[76:77]
	v_pk_mul_f32 v[14:15], v[94:95], v[8:9] op_sel_hi:[1,0]
	v_pk_fma_f32 v[78:79], v[30:31], v[14:15], v[78:79]
	v_pk_mul_f32 v[14:15], v[96:97], v[8:9] op_sel_hi:[1,0]
	v_pk_fma_f32 v[80:81], v[32:33], v[14:15], v[80:81]
	v_pk_mul_f32 v[14:15], v[98:99], v[8:9] op_sel_hi:[1,0]
	v_pk_fma_f32 v[82:83], v[34:35], v[14:15], v[82:83]
	v_pk_mul_f32 v[14:15], v[100:101], v[8:9] op_sel_hi:[1,0]
	v_pk_fma_f32 v[84:85], v[36:37], v[14:15], v[84:85]
	v_pk_mul_f32 v[12:13], v[70:71], v[70:71]
	v_pk_fma_f32 v[12:13], v[72:73], v[72:73], v[12:13]
	v_pk_fma_f32 v[12:13], v[74:75], v[74:75], v[12:13]
	v_pk_fma_f32 v[12:13], v[76:77], v[76:77], v[12:13]
	v_pk_fma_f32 v[12:13], v[78:79], v[78:79], v[12:13]
	v_pk_fma_f32 v[12:13], v[80:81], v[80:81], v[12:13]
	v_pk_fma_f32 v[12:13], v[82:83], v[82:83], v[12:13]
	v_pk_fma_f32 v[12:13], v[84:85], v[84:85], v[12:13]
	v_add_f32_e32 v5, v12, v13
	s_nop 1
	v_add_f32_dpp v5, v5, v5 quad_perm:[1,0,3,2] row_mask:0xf bank_mask:0xf
	s_nop 1
	v_add_f32_dpp v5, v5, v5 quad_perm:[2,3,0,1] row_mask:0xf bank_mask:0xf
	s_nop 1
	v_add_f32_dpp v5, v5, v5 row_half_mirror row_mask:0xf bank_mask:0xf
	s_nop 1
	v_add_f32_dpp v5, v5, v5 row_mirror row_mask:0xf bank_mask:0xf
	s_nop 1
	v_add_f32_dpp v5, v5, v5 row_bcast:15 row_mask:0xa bank_mask:0xf
	s_nop 1
	v_add_f32_dpp v5, v5, v5 row_bcast:31 row_mask:0xc bank_mask:0xf
	s_nop 1
	v_readlane_b32 s32, v5, 63
	s_nop 1
	v_mov_b32_e32 v6, s32
	v_fmamk_f32 v6, v6, 0x3a800000, v146
	v_rsq_f32_e32 v6, v6
	s_nop 0
	v_mov_b32_e32 v10, v6
	v_pk_mul_f32 v[14:15], v[70:71], v[10:11] op_sel_hi:[1,0]
	v_pk_fma_f32 v[16:17], v[54:55], v[14:15], v[38:39]
	v_pk_mul_f32 v[14:15], v[72:73], v[10:11] op_sel_hi:[1,0]
	v_pk_fma_f32 v[18:19], v[56:57], v[14:15], v[40:41]
	v_cvt_pk_bf16_f32 v86, v16, v17
	v_cvt_pk_bf16_f32 v87, v18, v19
	v_pk_mul_f32 v[14:15], v[74:75], v[10:11] op_sel_hi:[1,0]
	v_pk_fma_f32 v[16:17], v[58:59], v[14:15], v[42:43]
	v_pk_mul_f32 v[14:15], v[76:77], v[10:11] op_sel_hi:[1,0]
	v_pk_fma_f32 v[18:19], v[60:61], v[14:15], v[44:45]
	v_cvt_pk_bf16_f32 v90, v16, v17
	v_cvt_pk_bf16_f32 v91, v18, v19
	v_pk_mul_f32 v[14:15], v[78:79], v[10:11] op_sel_hi:[1,0]
	v_pk_fma_f32 v[16:17], v[62:63], v[14:15], v[46:47]
	v_pk_mul_f32 v[14:15], v[80:81], v[10:11] op_sel_hi:[1,0]
	v_pk_fma_f32 v[18:19], v[64:65], v[14:15], v[48:49]
	v_cvt_pk_bf16_f32 v94, v16, v17
	v_cvt_pk_bf16_f32 v95, v18, v19
	v_pk_mul_f32 v[14:15], v[82:83], v[10:11] op_sel_hi:[1,0]
	v_pk_fma_f32 v[16:17], v[66:67], v[14:15], v[50:51]
	v_pk_mul_f32 v[14:15], v[84:85], v[10:11] op_sel_hi:[1,0]
	v_pk_fma_f32 v[18:19], v[68:69], v[14:15], v[52:53]
	v_cvt_pk_bf16_f32 v98, v16, v17
	v_cvt_pk_bf16_f32 v99, v18, v19
	global_store_dwordx2 v1, v[86:87], s[62:63] offset:0 sc1
	global_store_dwordx2 v1, v[90:91], s[62:63] offset:512 sc1
	global_store_dwordx2 v1, v[94:95], s[62:63] offset:1024 sc1
	global_store_dwordx2 v1, v[98:99], s[62:63] offset:1536 sc1
	global_store_dwordx4 v0, v[70:73], s[46:47] offset:0
	global_store_dwordx4 v0, v[74:77], s[46:47] offset:1024
	global_store_dwordx4 v0, v[78:81], s[46:47] offset:2048
	global_store_dwordx4 v0, v[82:85], s[46:47] offset:3072
	s_add_u32 s46, s46, 0x1000
	s_addc_u32 s47, s47, 0
	s_add_u32 s62, s62, 0x800
	s_addc_u32 s63, s63, 0
	s_waitcnt vmcnt(24)
	v_lshlrev_b32_e32 v14, 16, v118
	v_and_b32_e32 v15, 0xffff0000, v118
	v_lshlrev_b32_e32 v16, 16, v120
	v_and_b32_e32 v17, 0xffff0000, v120
	v_lshlrev_b32_e32 v18, 16, v119
	v_and_b32_e32 v19, 0xffff0000, v119
	v_lshlrev_b32_e32 v20, 16, v121
	v_and_b32_e32 v21, 0xffff0000, v121
	v_pk_add_f32 v[118:119], v[14:15], v[16:17]
	v_pk_add_f32 v[120:121], v[18:19], v[20:21]
	v_lshlrev_b32_e32 v14, 16, v122
	v_and_b32_e32 v15, 0xffff0000, v122
	v_lshlrev_b32_e32 v16, 16, v124
	v_and_b32_e32 v17, 0xffff0000, v124
	v_lshlrev_b32_e32 v18, 16, v123
	v_and_b32_e32 v19, 0xffff0000, v123
	v_lshlrev_b32_e32 v20, 16, v125
	v_and_b32_e32 v21, 0xffff0000, v125
	v_pk_add_f32 v[122:123], v[14:15], v[16:17]
	v_pk_add_f32 v[124:125], v[18:19], v[20:21]
	v_lshlrev_b32_e32 v14, 16, v134
	v_and_b32_e32 v15, 0xffff0000, v134
	v_lshlrev_b32_e32 v16, 16, v136
	v_and_b32_e32 v17, 0xffff0000, v136
	v_lshlrev_b32_e32 v18, 16, v135
	v_and_b32_e32 v19, 0xffff0000, v135
	v_lshlrev_b32_e32 v20, 16, v137
	v_and_b32_e32 v21, 0xffff0000, v137
	v_pk_add_f32 v[134:135], v[14:15], v[16:17]
	v_pk_add_f32 v[136:137], v[18:19], v[20:21]
	v_lshlrev_b32_e32 v14, 16, v138
	v_and_b32_e32 v15, 0xffff0000, v138
	v_lshlrev_b32_e32 v16, 16, v140
	v_and_b32_e32 v17, 0xffff0000, v140
	v_lshlrev_b32_e32 v18, 16, v139
	v_and_b32_e32 v19, 0xffff0000, v139
	v_lshlrev_b32_e32 v20, 16, v141
	v_and_b32_e32 v21, 0xffff0000, v141
	v_pk_add_f32 v[138:139], v[14:15], v[16:17]
	v_pk_add_f32 v[140:141], v[18:19], v[20:21]
	v_pk_mul_f32 v[12:13], v[118:119], v[118:119]
	v_pk_fma_f32 v[12:13], v[120:121], v[120:121], v[12:13]
	v_pk_fma_f32 v[12:13], v[122:123], v[122:123], v[12:13]
	v_pk_fma_f32 v[12:13], v[124:125], v[124:125], v[12:13]
	v_pk_fma_f32 v[12:13], v[134:135], v[134:135], v[12:13]
	v_pk_fma_f32 v[12:13], v[136:137], v[136:137], v[12:13]
	v_pk_fma_f32 v[12:13], v[138:139], v[138:139], v[12:13]
	v_pk_fma_f32 v[12:13], v[140:141], v[140:141], v[12:13]
	v_add_f32_e32 v5, v12, v13
	s_nop 1
	v_add_f32_dpp v5, v5, v5 quad_perm:[1,0,3,2] row_mask:0xf bank_mask:0xf
	s_nop 1
	v_add_f32_dpp v5, v5, v5 quad_perm:[2,3,0,1] row_mask:0xf bank_mask:0xf
	s_nop 1
	v_add_f32_dpp v5, v5, v5 row_half_mirror row_mask:0xf bank_mask:0xf
	s_nop 1
	v_add_f32_dpp v5, v5, v5 row_mirror row_mask:0xf bank_mask:0xf
	s_nop 1
	v_add_f32_dpp v5, v5, v5 row_bcast:15 row_mask:0xa bank_mask:0xf
	s_nop 1
	v_add_f32_dpp v5, v5, v5 row_bcast:31 row_mask:0xc bank_mask:0xf
	s_nop 1
	v_readlane_b32 s32, v5, 63
	s_nop 1
	v_mov_b32_e32 v6, s32
	v_fmamk_f32 v6, v6, 0x3a800000, v146
	v_rsq_f32_e32 v6, v6
	s_nop 0
	v_mul_f32_e32 v8, 0.5, v6
	v_pk_mul_f32 v[14:15], v[118:119], v[8:9] op_sel_hi:[1,0]
	v_pk_fma_f32 v[102:103], v[22:23], v[14:15], v[102:103]
	v_pk_mul_f32 v[14:15], v[120:121], v[8:9] op_sel_hi:[1,0]
	v_pk_fma_f32 v[104:105], v[24:25], v[14:15], v[104:105]
	v_pk_mul_f32 v[14:15], v[122:123], v[8:9] op_sel_hi:[1,0]
	v_pk_fma_f32 v[106:107], v[26:27], v[14:15], v[106:107]
	v_pk_mul_f32 v[14:15], v[124:125], v[8:9] op_sel_hi:[1,0]
	v_pk_fma_f32 v[108:109], v[28:29], v[14:15], v[108:109]
	v_pk_mul_f32 v[14:15], v[134:135], v[8:9] op_sel_hi:[1,0]
	v_pk_fma_f32 v[110:111], v[30:31], v[14:15], v[110:111]
	v_pk_mul_f32 v[14:15], v[136:137], v[8:9] op_sel_hi:[1,0]
	v_pk_fma_f32 v[112:113], v[32:33], v[14:15], v[112:113]
	v_pk_mul_f32 v[14:15], v[138:139], v[8:9] op_sel_hi:[1,0]
	v_pk_fma_f32 v[114:115], v[34:35], v[14:15], v[114:115]
	v_pk_mul_f32 v[14:15], v[140:141], v[8:9] op_sel_hi:[1,0]
	v_pk_fma_f32 v[116:117], v[36:37], v[14:15], v[116:117]
	v_pk_mul_f32 v[12:13], v[102:103], v[102:103]
	v_pk_fma_f32 v[12:13], v[104:105], v[104:105], v[12:13]
	v_pk_fma_f32 v[12:13], v[106:107], v[106:107], v[12:13]
	v_pk_fma_f32 v[12:13], v[108:109], v[108:109], v[12:13]
	v_pk_fma_f32 v[12:13], v[110:111], v[110:111], v[12:13]
	v_pk_fma_f32 v[12:13], v[112:113], v[112:113], v[12:13]
	v_pk_fma_f32 v[12:13], v[114:115], v[114:115], v[12:13]
	v_pk_fma_f32 v[12:13], v[116:117], v[116:117], v[12:13]
	v_add_f32_e32 v5, v12, v13
	s_nop 1
	v_add_f32_dpp v5, v5, v5 quad_perm:[1,0,3,2] row_mask:0xf bank_mask:0xf
	s_nop 1
	v_add_f32_dpp v5, v5, v5 quad_perm:[2,3,0,1] row_mask:0xf bank_mask:0xf
	s_nop 1
	v_add_f32_dpp v5, v5, v5 row_half_mirror row_mask:0xf bank_mask:0xf
	s_nop 1
	v_add_f32_dpp v5, v5, v5 row_mirror row_mask:0xf bank_mask:0xf
	s_nop 1
	v_add_f32_dpp v5, v5, v5 row_bcast:15 row_mask:0xa bank_mask:0xf
	s_nop 1
	v_add_f32_dpp v5, v5, v5 row_bcast:31 row_mask:0xc bank_mask:0xf
	s_nop 1
	v_readlane_b32 s32, v5, 63
	s_nop 1
	v_mov_b32_e32 v6, s32
	v_fmamk_f32 v6, v6, 0x3a800000, v146
	v_rsq_f32_e32 v6, v6
	s_nop 0
	v_mov_b32_e32 v10, v6
	v_pk_mul_f32 v[14:15], v[102:103], v[10:11] op_sel_hi:[1,0]
	v_pk_fma_f32 v[16:17], v[54:55], v[14:15], v[38:39]
	v_pk_mul_f32 v[14:15], v[104:105], v[10:11] op_sel_hi:[1,0]
	v_pk_fma_f32 v[18:19], v[56:57], v[14:15], v[40:41]
	v_cvt_pk_bf16_f32 v118, v16, v17
	v_cvt_pk_bf16_f32 v119, v18, v19
	v_pk_mul_f32 v[14:15], v[106:107], v[10:11] op_sel_hi:[1,0]
	v_pk_fma_f32 v[16:17], v[58:59], v[14:15], v[42:43]
	v_pk_mul_f32 v[14:15], v[108:109], v[10:11] op_sel_hi:[1,0]
	v_pk_fma_f32 v[18:19], v[60:61], v[14:15], v[44:45]
	v_cvt_pk_bf16_f32 v122, v16, v17
	v_cvt_pk_bf16_f32 v123, v18, v19
	v_pk_mul_f32 v[14:15], v[110:111], v[10:11] op_sel_hi:[1,0]
	v_pk_fma_f32 v[16:17], v[62:63], v[14:15], v[46:47]
	v_pk_mul_f32 v[14:15], v[112:113], v[10:11] op_sel_hi:[1,0]
	v_pk_fma_f32 v[18:19], v[64:65], v[14:15], v[48:49]
	v_cvt_pk_bf16_f32 v134, v16, v17
	v_cvt_pk_bf16_f32 v135, v18, v19
	v_pk_mul_f32 v[14:15], v[114:115], v[10:11] op_sel_hi:[1,0]
	v_pk_fma_f32 v[16:17], v[66:67], v[14:15], v[50:51]
	v_pk_mul_f32 v[14:15], v[116:117], v[10:11] op_sel_hi:[1,0]
	v_pk_fma_f32 v[18:19], v[68:69], v[14:15], v[52:53]
	v_cvt_pk_bf16_f32 v138, v16, v17
	v_cvt_pk_bf16_f32 v139, v18, v19
	global_store_dwordx2 v1, v[118:119], s[62:63] offset:0 sc1
	global_store_dwordx2 v1, v[122:123], s[62:63] offset:512 sc1
	global_store_dwordx2 v1, v[134:135], s[62:63] offset:1024 sc1
	global_store_dwordx2 v1, v[138:139], s[62:63] offset:1536 sc1
	global_store_dwordx4 v0, v[102:105], s[46:47] offset:0
	global_store_dwordx4 v0, v[106:109], s[46:47] offset:1024
	global_store_dwordx4 v0, v[110:113], s[46:47] offset:2048
	global_store_dwordx4 v0, v[114:117], s[46:47] offset:3072
	s_add_u32 s46, s46, 0x1000
	s_addc_u32 s47, s47, 0
	s_add_u32 s62, s62, 0x800
	s_addc_u32 s63, s63, 0
	s_waitcnt vmcnt(24)
	v_lshlrev_b32_e32 v14, 16, v172
	v_and_b32_e32 v15, 0xffff0000, v172
	v_lshlrev_b32_e32 v16, 16, v174
	v_and_b32_e32 v17, 0xffff0000, v174
	v_lshlrev_b32_e32 v18, 16, v173
	v_and_b32_e32 v19, 0xffff0000, v173
	v_lshlrev_b32_e32 v20, 16, v175
	v_and_b32_e32 v21, 0xffff0000, v175
	v_pk_add_f32 v[172:173], v[14:15], v[16:17]
	v_pk_add_f32 v[174:175], v[18:19], v[20:21]
	v_lshlrev_b32_e32 v14, 16, v176
	v_and_b32_e32 v15, 0xffff0000, v176
	v_lshlrev_b32_e32 v16, 16, v178
	v_and_b32_e32 v17, 0xffff0000, v178
	v_lshlrev_b32_e32 v18, 16, v177
	v_and_b32_e32 v19, 0xffff0000, v177
	v_lshlrev_b32_e32 v20, 16, v179
	v_and_b32_e32 v21, 0xffff0000, v179
	v_pk_add_f32 v[176:177], v[14:15], v[16:17]
	v_pk_add_f32 v[178:179], v[18:19], v[20:21]
	v_lshlrev_b32_e32 v14, 16, v204
	v_and_b32_e32 v15, 0xffff0000, v204
	v_lshlrev_b32_e32 v16, 16, v206
	v_and_b32_e32 v17, 0xffff0000, v206
	v_lshlrev_b32_e32 v18, 16, v205
	v_and_b32_e32 v19, 0xffff0000, v205
	v_lshlrev_b32_e32 v20, 16, v207
	v_and_b32_e32 v21, 0xffff0000, v207
	v_pk_add_f32 v[204:205], v[14:15], v[16:17]
	v_pk_add_f32 v[206:207], v[18:19], v[20:21]
	v_lshlrev_b32_e32 v14, 16, v214
	v_and_b32_e32 v15, 0xffff0000, v214
	v_lshlrev_b32_e32 v16, 16, v216
	v_and_b32_e32 v17, 0xffff0000, v216
	v_lshlrev_b32_e32 v18, 16, v215
	v_and_b32_e32 v19, 0xffff0000, v215
	v_lshlrev_b32_e32 v20, 16, v217
	v_and_b32_e32 v21, 0xffff0000, v217
	v_pk_add_f32 v[214:215], v[14:15], v[16:17]
	v_pk_add_f32 v[216:217], v[18:19], v[20:21]
	v_pk_mul_f32 v[12:13], v[172:173], v[172:173]
	v_pk_fma_f32 v[12:13], v[174:175], v[174:175], v[12:13]
	v_pk_fma_f32 v[12:13], v[176:177], v[176:177], v[12:13]
	v_pk_fma_f32 v[12:13], v[178:179], v[178:179], v[12:13]
	v_pk_fma_f32 v[12:13], v[204:205], v[204:205], v[12:13]
	v_pk_fma_f32 v[12:13], v[206:207], v[206:207], v[12:13]
	v_pk_fma_f32 v[12:13], v[214:215], v[214:215], v[12:13]
	v_pk_fma_f32 v[12:13], v[216:217], v[216:217], v[12:13]
	v_add_f32_e32 v5, v12, v13
	s_nop 1
	v_add_f32_dpp v5, v5, v5 quad_perm:[1,0,3,2] row_mask:0xf bank_mask:0xf
	s_nop 1
	v_add_f32_dpp v5, v5, v5 quad_perm:[2,3,0,1] row_mask:0xf bank_mask:0xf
	s_nop 1
	v_add_f32_dpp v5, v5, v5 row_half_mirror row_mask:0xf bank_mask:0xf
	s_nop 1
	v_add_f32_dpp v5, v5, v5 row_mirror row_mask:0xf bank_mask:0xf
	s_nop 1
	v_add_f32_dpp v5, v5, v5 row_bcast:15 row_mask:0xa bank_mask:0xf
	s_nop 1
	v_add_f32_dpp v5, v5, v5 row_bcast:31 row_mask:0xc bank_mask:0xf
	s_nop 1
	v_readlane_b32 s32, v5, 63
	s_nop 1
	v_mov_b32_e32 v6, s32
	v_fmamk_f32 v6, v6, 0x3a800000, v146
	v_rsq_f32_e32 v6, v6
	s_nop 0
	v_mul_f32_e32 v8, 0.5, v6
	v_pk_mul_f32 v[14:15], v[172:173], v[8:9] op_sel_hi:[1,0]
	v_pk_fma_f32 v[154:155], v[22:23], v[14:15], v[154:155]
	v_pk_mul_f32 v[14:15], v[174:175], v[8:9] op_sel_hi:[1,0]
	v_pk_fma_f32 v[156:157], v[24:25], v[14:15], v[156:157]
	v_pk_mul_f32 v[14:15], v[176:177], v[8:9] op_sel_hi:[1,0]
	v_pk_fma_f32 v[158:159], v[26:27], v[14:15], v[158:159]
	v_pk_mul_f32 v[14:15], v[178:179], v[8:9] op_sel_hi:[1,0]
	v_pk_fma_f32 v[160:161], v[28:29], v[14:15], v[160:161]
	v_pk_mul_f32 v[14:15], v[204:205], v[8:9] op_sel_hi:[1,0]
	v_pk_fma_f32 v[162:163], v[30:31], v[14:15], v[162:163]
	v_pk_mul_f32 v[14:15], v[206:207], v[8:9] op_sel_hi:[1,0]
	v_pk_fma_f32 v[164:165], v[32:33], v[14:15], v[164:165]
	v_pk_mul_f32 v[14:15], v[214:215], v[8:9] op_sel_hi:[1,0]
	v_pk_fma_f32 v[168:169], v[34:35], v[14:15], v[168:169]
	v_pk_mul_f32 v[14:15], v[216:217], v[8:9] op_sel_hi:[1,0]
	v_pk_fma_f32 v[170:171], v[36:37], v[14:15], v[170:171]
	v_pk_mul_f32 v[12:13], v[154:155], v[154:155]
	v_pk_fma_f32 v[12:13], v[156:157], v[156:157], v[12:13]
	v_pk_fma_f32 v[12:13], v[158:159], v[158:159], v[12:13]
	v_pk_fma_f32 v[12:13], v[160:161], v[160:161], v[12:13]
	v_pk_fma_f32 v[12:13], v[162:163], v[162:163], v[12:13]
	v_pk_fma_f32 v[12:13], v[164:165], v[164:165], v[12:13]
	v_pk_fma_f32 v[12:13], v[168:169], v[168:169], v[12:13]
	v_pk_fma_f32 v[12:13], v[170:171], v[170:171], v[12:13]
	v_add_f32_e32 v5, v12, v13
	s_nop 1
	v_add_f32_dpp v5, v5, v5 quad_perm:[1,0,3,2] row_mask:0xf bank_mask:0xf
	s_nop 1
	v_add_f32_dpp v5, v5, v5 quad_perm:[2,3,0,1] row_mask:0xf bank_mask:0xf
	s_nop 1
	v_add_f32_dpp v5, v5, v5 row_half_mirror row_mask:0xf bank_mask:0xf
	s_nop 1
	v_add_f32_dpp v5, v5, v5 row_mirror row_mask:0xf bank_mask:0xf
	s_nop 1
	v_add_f32_dpp v5, v5, v5 row_bcast:15 row_mask:0xa bank_mask:0xf
	s_nop 1
	v_add_f32_dpp v5, v5, v5 row_bcast:31 row_mask:0xc bank_mask:0xf
	s_nop 1
	v_readlane_b32 s32, v5, 63
	s_nop 1
	v_mov_b32_e32 v6, s32
	v_fmamk_f32 v6, v6, 0x3a800000, v146
	v_rsq_f32_e32 v6, v6
	s_nop 0
	v_mov_b32_e32 v10, v6
	v_pk_mul_f32 v[14:15], v[154:155], v[10:11] op_sel_hi:[1,0]
	v_pk_fma_f32 v[16:17], v[54:55], v[14:15], v[38:39]
	v_pk_mul_f32 v[14:15], v[156:157], v[10:11] op_sel_hi:[1,0]
	v_pk_fma_f32 v[18:19], v[56:57], v[14:15], v[40:41]
	v_cvt_pk_bf16_f32 v172, v16, v17
	v_cvt_pk_bf16_f32 v173, v18, v19
	v_pk_mul_f32 v[14:15], v[158:159], v[10:11] op_sel_hi:[1,0]
	v_pk_fma_f32 v[16:17], v[58:59], v[14:15], v[42:43]
	v_pk_mul_f32 v[14:15], v[160:161], v[10:11] op_sel_hi:[1,0]
	v_pk_fma_f32 v[18:19], v[60:61], v[14:15], v[44:45]
	v_cvt_pk_bf16_f32 v176, v16, v17
	v_cvt_pk_bf16_f32 v177, v18, v19
	v_pk_mul_f32 v[14:15], v[162:163], v[10:11] op_sel_hi:[1,0]
	v_pk_fma_f32 v[16:17], v[62:63], v[14:15], v[46:47]
	v_pk_mul_f32 v[14:15], v[164:165], v[10:11] op_sel_hi:[1,0]
	v_pk_fma_f32 v[18:19], v[64:65], v[14:15], v[48:49]
	v_cvt_pk_bf16_f32 v204, v16, v17
	v_cvt_pk_bf16_f32 v205, v18, v19
	v_pk_mul_f32 v[14:15], v[168:169], v[10:11] op_sel_hi:[1,0]
	v_pk_fma_f32 v[16:17], v[66:67], v[14:15], v[50:51]
	v_pk_mul_f32 v[14:15], v[170:171], v[10:11] op_sel_hi:[1,0]
	v_pk_fma_f32 v[18:19], v[68:69], v[14:15], v[52:53]
	v_cvt_pk_bf16_f32 v214, v16, v17
	v_cvt_pk_bf16_f32 v215, v18, v19
	global_store_dwordx2 v1, v[172:173], s[62:63] offset:0 sc1
	global_store_dwordx2 v1, v[176:177], s[62:63] offset:512 sc1
	global_store_dwordx2 v1, v[204:205], s[62:63] offset:1024 sc1
	global_store_dwordx2 v1, v[214:215], s[62:63] offset:1536 sc1
	global_store_dwordx4 v0, v[154:157], s[46:47] offset:0
	global_store_dwordx4 v0, v[158:161], s[46:47] offset:1024
	global_store_dwordx4 v0, v[162:165], s[46:47] offset:2048
	global_store_dwordx4 v0, v[168:171], s[46:47] offset:3072
	s_add_u32 s46, s46, 0x1000
	s_addc_u32 s47, s47, 0
	s_add_u32 s62, s62, 0x800
	s_addc_u32 s63, s63, 0
	s_waitcnt vmcnt(24)
	v_lshlrev_b32_e32 v14, 16, v234
	v_and_b32_e32 v15, 0xffff0000, v234
	v_lshlrev_b32_e32 v16, 16, v236
	v_and_b32_e32 v17, 0xffff0000, v236
	v_lshlrev_b32_e32 v18, 16, v235
	v_and_b32_e32 v19, 0xffff0000, v235
	v_lshlrev_b32_e32 v20, 16, v237
	v_and_b32_e32 v21, 0xffff0000, v237
	v_pk_add_f32 v[234:235], v[14:15], v[16:17]
	v_pk_add_f32 v[236:237], v[18:19], v[20:21]
	v_lshlrev_b32_e32 v14, 16, v238
	v_and_b32_e32 v15, 0xffff0000, v238
	v_lshlrev_b32_e32 v16, 16, v240
	v_and_b32_e32 v17, 0xffff0000, v240
	v_lshlrev_b32_e32 v18, 16, v239
	v_and_b32_e32 v19, 0xffff0000, v239
	v_lshlrev_b32_e32 v20, 16, v241
	v_and_b32_e32 v21, 0xffff0000, v241
	v_pk_add_f32 v[238:239], v[14:15], v[16:17]
	v_pk_add_f32 v[240:241], v[18:19], v[20:21]
	v_lshlrev_b32_e32 v14, 16, v242
	v_and_b32_e32 v15, 0xffff0000, v242
	v_lshlrev_b32_e32 v16, 16, v244
	v_and_b32_e32 v17, 0xffff0000, v244
	v_lshlrev_b32_e32 v18, 16, v243
	v_and_b32_e32 v19, 0xffff0000, v243
	v_lshlrev_b32_e32 v20, 16, v245
	v_and_b32_e32 v21, 0xffff0000, v245
	v_pk_add_f32 v[242:243], v[14:15], v[16:17]
	v_pk_add_f32 v[244:245], v[18:19], v[20:21]
	v_lshlrev_b32_e32 v14, 16, v246
	v_and_b32_e32 v15, 0xffff0000, v246
	v_lshlrev_b32_e32 v16, 16, v248
	v_and_b32_e32 v17, 0xffff0000, v248
	v_lshlrev_b32_e32 v18, 16, v247
	v_and_b32_e32 v19, 0xffff0000, v247
	v_lshlrev_b32_e32 v20, 16, v249
	v_and_b32_e32 v21, 0xffff0000, v249
	v_pk_add_f32 v[246:247], v[14:15], v[16:17]
	v_pk_add_f32 v[248:249], v[18:19], v[20:21]
	v_pk_mul_f32 v[12:13], v[234:235], v[234:235]
	v_pk_fma_f32 v[12:13], v[236:237], v[236:237], v[12:13]
	v_pk_fma_f32 v[12:13], v[238:239], v[238:239], v[12:13]
	v_pk_fma_f32 v[12:13], v[240:241], v[240:241], v[12:13]
	v_pk_fma_f32 v[12:13], v[242:243], v[242:243], v[12:13]
	v_pk_fma_f32 v[12:13], v[244:245], v[244:245], v[12:13]
	v_pk_fma_f32 v[12:13], v[246:247], v[246:247], v[12:13]
	v_pk_fma_f32 v[12:13], v[248:249], v[248:249], v[12:13]
	v_add_f32_e32 v5, v12, v13
	s_nop 1
	v_add_f32_dpp v5, v5, v5 quad_perm:[1,0,3,2] row_mask:0xf bank_mask:0xf
	s_nop 1
	v_add_f32_dpp v5, v5, v5 quad_perm:[2,3,0,1] row_mask:0xf bank_mask:0xf
	s_nop 1
	v_add_f32_dpp v5, v5, v5 row_half_mirror row_mask:0xf bank_mask:0xf
	s_nop 1
	v_add_f32_dpp v5, v5, v5 row_mirror row_mask:0xf bank_mask:0xf
	s_nop 1
	v_add_f32_dpp v5, v5, v5 row_bcast:15 row_mask:0xa bank_mask:0xf
	s_nop 1
	v_add_f32_dpp v5, v5, v5 row_bcast:31 row_mask:0xc bank_mask:0xf
	s_nop 1
	v_readlane_b32 s32, v5, 63
	s_nop 1
	v_mov_b32_e32 v6, s32
	v_fmamk_f32 v6, v6, 0x3a800000, v146
	v_rsq_f32_e32 v6, v6
	s_nop 0
	v_mul_f32_e32 v8, 0.5, v6
	v_pk_mul_f32 v[14:15], v[234:235], v[8:9] op_sel_hi:[1,0]
	v_pk_fma_f32 v[218:219], v[22:23], v[14:15], v[218:219]
	v_pk_mul_f32 v[14:15], v[236:237], v[8:9] op_sel_hi:[1,0]
	v_pk_fma_f32 v[220:221], v[24:25], v[14:15], v[220:221]
	v_pk_mul_f32 v[14:15], v[238:239], v[8:9] op_sel_hi:[1,0]
	v_pk_fma_f32 v[222:223], v[26:27], v[14:15], v[222:223]
	v_pk_mul_f32 v[14:15], v[240:241], v[8:9] op_sel_hi:[1,0]
	v_pk_fma_f32 v[224:225], v[28:29], v[14:15], v[224:225]
	v_pk_mul_f32 v[14:15], v[242:243], v[8:9] op_sel_hi:[1,0]
	v_pk_fma_f32 v[226:227], v[30:31], v[14:15], v[226:227]
	v_pk_mul_f32 v[14:15], v[244:245], v[8:9] op_sel_hi:[1,0]
	v_pk_fma_f32 v[228:229], v[32:33], v[14:15], v[228:229]
	v_pk_mul_f32 v[14:15], v[246:247], v[8:9] op_sel_hi:[1,0]
	v_pk_fma_f32 v[230:231], v[34:35], v[14:15], v[230:231]
	v_pk_mul_f32 v[14:15], v[248:249], v[8:9] op_sel_hi:[1,0]
	v_pk_fma_f32 v[232:233], v[36:37], v[14:15], v[232:233]
	v_pk_mul_f32 v[12:13], v[218:219], v[218:219]
	v_pk_fma_f32 v[12:13], v[220:221], v[220:221], v[12:13]
	v_pk_fma_f32 v[12:13], v[222:223], v[222:223], v[12:13]
	v_pk_fma_f32 v[12:13], v[224:225], v[224:225], v[12:13]
	v_pk_fma_f32 v[12:13], v[226:227], v[226:227], v[12:13]
	v_pk_fma_f32 v[12:13], v[228:229], v[228:229], v[12:13]
	v_pk_fma_f32 v[12:13], v[230:231], v[230:231], v[12:13]
	v_pk_fma_f32 v[12:13], v[232:233], v[232:233], v[12:13]
	v_add_f32_e32 v5, v12, v13
	s_nop 1
	v_add_f32_dpp v5, v5, v5 quad_perm:[1,0,3,2] row_mask:0xf bank_mask:0xf
	s_nop 1
	v_add_f32_dpp v5, v5, v5 quad_perm:[2,3,0,1] row_mask:0xf bank_mask:0xf
	s_nop 1
	v_add_f32_dpp v5, v5, v5 row_half_mirror row_mask:0xf bank_mask:0xf
	s_nop 1
	v_add_f32_dpp v5, v5, v5 row_mirror row_mask:0xf bank_mask:0xf
	s_nop 1
	v_add_f32_dpp v5, v5, v5 row_bcast:15 row_mask:0xa bank_mask:0xf
	s_nop 1
	v_add_f32_dpp v5, v5, v5 row_bcast:31 row_mask:0xc bank_mask:0xf
	s_nop 1
	v_readlane_b32 s32, v5, 63
	s_nop 1
	v_mov_b32_e32 v6, s32
	v_fmamk_f32 v6, v6, 0x3a800000, v146
	v_rsq_f32_e32 v6, v6
	s_nop 0
	v_mov_b32_e32 v10, v6
	v_pk_mul_f32 v[14:15], v[218:219], v[10:11] op_sel_hi:[1,0]
	v_pk_fma_f32 v[16:17], v[54:55], v[14:15], v[38:39]
	v_pk_mul_f32 v[14:15], v[220:221], v[10:11] op_sel_hi:[1,0]
	v_pk_fma_f32 v[18:19], v[56:57], v[14:15], v[40:41]
	v_cvt_pk_bf16_f32 v234, v16, v17
	v_cvt_pk_bf16_f32 v235, v18, v19
	v_pk_mul_f32 v[14:15], v[222:223], v[10:11] op_sel_hi:[1,0]
	v_pk_fma_f32 v[16:17], v[58:59], v[14:15], v[42:43]
	v_pk_mul_f32 v[14:15], v[224:225], v[10:11] op_sel_hi:[1,0]
	v_pk_fma_f32 v[18:19], v[60:61], v[14:15], v[44:45]
	v_cvt_pk_bf16_f32 v238, v16, v17
	v_cvt_pk_bf16_f32 v239, v18, v19
	v_pk_mul_f32 v[14:15], v[226:227], v[10:11] op_sel_hi:[1,0]
	v_pk_fma_f32 v[16:17], v[62:63], v[14:15], v[46:47]
	v_pk_mul_f32 v[14:15], v[228:229], v[10:11] op_sel_hi:[1,0]
	v_pk_fma_f32 v[18:19], v[64:65], v[14:15], v[48:49]
	v_cvt_pk_bf16_f32 v242, v16, v17
	v_cvt_pk_bf16_f32 v243, v18, v19
	v_pk_mul_f32 v[14:15], v[230:231], v[10:11] op_sel_hi:[1,0]
	v_pk_fma_f32 v[16:17], v[66:67], v[14:15], v[50:51]
	v_pk_mul_f32 v[14:15], v[232:233], v[10:11] op_sel_hi:[1,0]
	v_pk_fma_f32 v[18:19], v[68:69], v[14:15], v[52:53]
	v_cvt_pk_bf16_f32 v246, v16, v17
	v_cvt_pk_bf16_f32 v247, v18, v19
	global_store_dwordx2 v1, v[234:235], s[62:63] offset:0 sc1
	global_store_dwordx2 v1, v[238:239], s[62:63] offset:512 sc1
	global_store_dwordx2 v1, v[242:243], s[62:63] offset:1024 sc1
	global_store_dwordx2 v1, v[246:247], s[62:63] offset:1536 sc1
	global_store_dwordx4 v0, v[218:221], s[46:47] offset:0
	global_store_dwordx4 v0, v[222:225], s[46:47] offset:1024
	global_store_dwordx4 v0, v[226:229], s[46:47] offset:2048
	global_store_dwordx4 v0, v[230:233], s[46:47] offset:3072
	s_add_u32 s46, s46, 0x1000
	s_addc_u32 s47, s47, 0
	s_add_u32 s62, s62, 0x800
	s_addc_u32 s63, s63, 0
	s_branch .Lnorm0_done

.Lnorm0_done:
.LBB0_280:
	s_or_b64 exec, exec, s[16:17]
	s_mov_b64 s[8:9], s[0:1]
	s_waitcnt vmcnt(0)
	v_mov_b32_e32 v0, v147
	s_barrier
	s_nop 0
	v_readfirstlane_b32 vcc_lo, v0
	s_nop 1
	s_cmp_eq_u32 vcc_lo, 64
	s_cbranch_scc0 .Lxb_noinv_1
	buffer_inv sc1
.Lxb_noinv_1:
	v_cmp_eq_u32_e32 vcc, 0, v0
	s_and_saveexec_b64 s[0:1], vcc
	s_cbranch_execz .LBB0_332
	s_load_dwordx2 s[12:13], s[8:9], 0x98
	v_readlane_b32 s14, v255, 0
	v_readlane_b32 s15, v255, 48
	s_nop 0
	s_lshr_b32 s24, s14, 3
	s_and_b32 s24, s24, 7
	s_and_b32 s27, s14, 6
	s_lshl_b32 s27, s27, 2
	s_or_b32 s27, s27, s24
	s_and_b32 s30, s14, 3
	s_lshl_b32 s30, s30, 3
	s_or_b32 s30, s30, s24
	s_lshl_b32 s27, s27, 7
	s_add_u32 s27, s27, 0xc000
	v_readlane_b32 s35, v255, 45
	s_nop 0
	s_lshl_b32 s35, s35, 4
	s_add_u32 s15, s15, 8
	v_writelane_b32 v255, s15, 48
	v_mov_b32_e32 v0, s27
	s_waitcnt lgkmcnt(0)
	global_atomic_add v0, v189, s[12:13]
	v_writelane_b32 v255, s27, 50
	v_writelane_b32 v255, s15, 51
	s_mov_b32 s34, 0xd000
	v_writelane_b32 v255, s34, 52
	v_writelane_b32 v255, s35, 53
	v_writelane_b32 v255, s12, 54
	v_writelane_b32 v255, s13, 55

.Lgw_skip_fi:
	s_or_b64 exec, exec, s[100:101]
	s_waitcnt vmcnt(4)
	s_barrier
	s_mov_b32 m0, s38
	s_add_u32 s4, s54, 0x40000
	global_load_lds_dwordx4 v132, s[54:55]
	s_mov_b32 m0, s40
	s_addc_u32 s5, s55, 0
	s_add_i32 s41, s38, 0x4000
	global_load_lds_dwordx4 v130, s[54:55]
	s_mov_b32 m0, s41
	s_add_i32 s44, s38, 0x6000
	global_load_lds_dwordx4 v132, s[4:5]
	s_mov_b32 m0, s44
	v_mov_b32_e32 v133, v145
	global_load_lds_dwordx4 v130, s[4:5]
	v_mov_b32_e32 v131, v145
	s_cmp_eq_u32 s13, 1
	v_lshl_add_u64 v[6:7], s[42:43], 0, v[144:145]
	v_lshl_add_u64 v[4:5], s[42:43], 0, v[128:129]
	v_lshl_add_u64 v[0:1], s[54:55], 0, v[132:133]
	s_cselect_b64 s[4:5], -1, 0
	s_cmp_lg_u32 s13, 1
	v_lshl_add_u64 v[2:3], s[54:55], 0, v[130:131]
	s_cbranch_scc1 .LBB0_339
	s_barrier

.LBB0_385:
	s_waitcnt vmcnt(0)
	v_mov_b32_e32 v0, v147
	s_waitcnt vmcnt(0)
	s_barrier
	s_nop 0
	v_readfirstlane_b32 vcc_lo, v0
	s_nop 1
	s_cmp_eq_u32 vcc_lo, 64
	s_cbranch_scc0 .Lxb_noinv_2
	buffer_inv sc1
.Lxb_noinv_2:
	v_cmp_eq_u32_e32 vcc, 0, v0
	s_and_saveexec_b64 s[0:1], vcc
	s_xor_b64 s[0:1], exec, s[0:1]
	s_cbranch_execz .LBB0_438
	s_load_dwordx2 s[12:13], s[8:9], 0x98
	v_readlane_b32 s14, v255, 0
	v_readlane_b32 s15, v255, 45
	s_nop 0
	s_lshr_b32 s24, s14, 3
	s_and_b32 s24, s24, 7
	s_and_b32 s27, s14, 6
	s_lshl_b32 s27, s27, 2
	s_or_b32 s27, s27, s24
	s_and_b32 s30, s14, 3
	s_lshl_b32 s30, s30, 3
	s_or_b32 s30, s30, s24
	s_lshl_b32 s27, s27, 1
	s_and_b32 s24, s14, 1
	s_or_b32 s27, s27, s24
	s_lshl_b32 s27, s27, 7
	s_add_u32 s27, s27, 0x8000
	s_lshl_b32 s30, s30, 1
	s_bfe_u32 s24, s14, 0x10002
	s_or_b32 s30, s30, s24
	s_lshl_b32 s30, s30, 7
	s_add_u32 s30, s30, 0x8000
	s_add_u32 s15, s15, 4
	v_writelane_b32 v255, s15, 45
	v_mov_b32_e32 v0, s27
	s_waitcnt lgkmcnt(0)
	global_atomic_add v0, v189, s[12:13]
	s_cmp_lt_u32 s14, 0xc0
	s_cbranch_scc1 .Lgs_nocw_b2
	v_mov_b32_e32 v10, 0xd000
	global_atomic_add v10, v189, s[12:13]

.Lgw_skip_fo:
	s_or_b64 exec, exec, s[100:101]
	s_waitcnt vmcnt(4)
	s_barrier
	s_mov_b32 m0, s37
	s_add_u32 s8, s18, 0xb0000
	global_load_lds_dwordx4 v128, s[18:19]
	s_mov_b32 m0, s40
	s_addc_u32 s9, s19, 0
	s_add_i32 s41, s37, 0x4000
	global_load_lds_dwordx4 v132, s[18:19]
	s_mov_b32 m0, s41
	s_add_i32 s42, s37, 0x6000
	global_load_lds_dwordx4 v128, s[8:9]
	s_mov_b32 m0, s42
	v_mov_b32_e32 v135, v145
	global_load_lds_dwordx4 v132, s[8:9]
	v_mov_b32_e32 v129, v145
	v_mov_b32_e32 v133, v145
	s_cmp_eq_u32 s6, 1
	v_lshl_add_u64 v[6:7], s[20:21], 0, v[130:131]
	v_lshl_add_u64 v[4:5], s[20:21], 0, v[134:135]
	v_lshl_add_u64 v[0:1], s[18:19], 0, v[128:129]
	s_cselect_b64 s[8:9], -1, 0
	s_cmp_lg_u32 s6, 1
	v_lshl_add_u64 v[2:3], s[18:19], 0, v[132:133]
	s_cbranch_scc1 .LBB0_445
	s_barrier

.LBB0_466:
	s_waitcnt vmcnt(0)
	v_mov_b32_e32 v0, v147
	s_waitcnt vmcnt(0)
	s_barrier
	s_nop 0
	v_readfirstlane_b32 vcc_lo, v0
	s_nop 1
	s_cmp_eq_u32 vcc_lo, 64
	s_cbranch_scc0 .Lxb_noinv_3
	buffer_inv sc1
.Lxb_noinv_3:
	v_cmp_eq_u32_e32 vcc, 0, v0
	s_and_saveexec_b64 s[4:5], vcc
	s_xor_b64 s[4:5], exec, s[4:5]
	s_cbranch_execz .LBB0_519
	s_load_dwordx2 s[12:13], s[0:1], 0x98
	v_readlane_b32 s14, v255, 0
	v_readlane_b32 s15, v255, 46
	s_nop 0
	s_lshr_b32 s24, s14, 3
	s_and_b32 s24, s24, 7
	s_and_b32 s27, s14, 6
	s_lshl_b32 s27, s27, 2
	s_or_b32 s27, s27, s24
	s_and_b32 s30, s14, 3
	s_lshl_b32 s30, s30, 3
	s_or_b32 s30, s30, s24
	s_lshl_b32 s27, s27, 7
	s_add_u32 s27, s27, 0xa000
	s_lshl_b32 s30, s30, 7
	s_add_u32 s30, s30, 0xa000
	s_add_u32 s15, s15, 8
	v_writelane_b32 v255, s15, 46
	v_mov_b32_e32 v0, s30
	s_waitcnt lgkmcnt(0)
	global_atomic_add v0, v189, s[12:13]

.Lnw_skip_n1:
	s_or_b64 exec, exec, s[40:41]
	s_waitcnt vmcnt(36)
	s_barrier
	global_load_dwordx2 v[86:87], v1, s[58:59] offset:0
	global_load_dwordx2 v[90:91], v1, s[58:59] offset:512
	global_load_dwordx2 v[94:95], v1, s[58:59] offset:1024
	global_load_dwordx2 v[98:99], v1, s[58:59] offset:1536
	global_load_dwordx2 v[88:89], v1, s[60:61] offset:0
	global_load_dwordx2 v[92:93], v1, s[60:61] offset:512
	global_load_dwordx2 v[96:97], v1, s[60:61] offset:1024
	global_load_dwordx2 v[100:101], v1, s[60:61] offset:1536
	s_add_u32 s58, s58, 0x800
	s_addc_u32 s59, s59, 0
	s_add_u32 s60, s60, 0x800
	s_addc_u32 s61, s61, 0
	global_load_dwordx2 v[118:119], v1, s[58:59] offset:0
	global_load_dwordx2 v[122:123], v1, s[58:59] offset:512
	global_load_dwordx2 v[134:135], v1, s[58:59] offset:1024
	global_load_dwordx2 v[138:139], v1, s[58:59] offset:1536
	global_load_dwordx2 v[120:121], v1, s[60:61] offset:0
	global_load_dwordx2 v[124:125], v1, s[60:61] offset:512
	global_load_dwordx2 v[136:137], v1, s[60:61] offset:1024
	global_load_dwordx2 v[140:141], v1, s[60:61] offset:1536
	s_add_u32 s58, s58, 0x800
	s_addc_u32 s59, s59, 0
	s_add_u32 s60, s60, 0x800
	s_addc_u32 s61, s61, 0
	global_load_dwordx2 v[172:173], v1, s[58:59] offset:0
	global_load_dwordx2 v[176:177], v1, s[58:59] offset:512
	global_load_dwordx2 v[204:205], v1, s[58:59] offset:1024
	global_load_dwordx2 v[214:215], v1, s[58:59] offset:1536
	global_load_dwordx2 v[174:175], v1, s[60:61] offset:0
	global_load_dwordx2 v[178:179], v1, s[60:61] offset:512
	global_load_dwordx2 v[206:207], v1, s[60:61] offset:1024
	global_load_dwordx2 v[216:217], v1, s[60:61] offset:1536
	s_add_u32 s58, s58, 0x800
	s_addc_u32 s59, s59, 0
	s_add_u32 s60, s60, 0x800
	s_addc_u32 s61, s61, 0
	global_load_dwordx2 v[234:235], v1, s[58:59] offset:0
	global_load_dwordx2 v[238:239], v1, s[58:59] offset:512
	global_load_dwordx2 v[242:243], v1, s[58:59] offset:1024
	global_load_dwordx2 v[246:247], v1, s[58:59] offset:1536
	global_load_dwordx2 v[236:237], v1, s[60:61] offset:0
	global_load_dwordx2 v[240:241], v1, s[60:61] offset:512
	global_load_dwordx2 v[244:245], v1, s[60:61] offset:1024
	global_load_dwordx2 v[248:249], v1, s[60:61] offset:1536
	s_add_u32 s58, s58, 0x800
	s_addc_u32 s59, s59, 0
	s_add_u32 s60, s60, 0x800
	s_addc_u32 s61, s61, 0
	s_waitcnt vmcnt(24)
	v_lshlrev_b32_e32 v14, 16, v86
	v_and_b32_e32 v15, 0xffff0000, v86
	v_lshlrev_b32_e32 v16, 16, v88
	v_and_b32_e32 v17, 0xffff0000, v88
	v_lshlrev_b32_e32 v18, 16, v87
	v_and_b32_e32 v19, 0xffff0000, v87
	v_lshlrev_b32_e32 v20, 16, v89
	v_and_b32_e32 v21, 0xffff0000, v89
	v_pk_add_f32 v[86:87], v[14:15], v[16:17]
	v_pk_add_f32 v[88:89], v[18:19], v[20:21]
	v_lshlrev_b32_e32 v14, 16, v90
	v_and_b32_e32 v15, 0xffff0000, v90
	v_lshlrev_b32_e32 v16, 16, v92
	v_and_b32_e32 v17, 0xffff0000, v92
	v_lshlrev_b32_e32 v18, 16, v91
	v_and_b32_e32 v19, 0xffff0000, v91
	v_lshlrev_b32_e32 v20, 16, v93
	v_and_b32_e32 v21, 0xffff0000, v93
	v_pk_add_f32 v[90:91], v[14:15], v[16:17]
	v_pk_add_f32 v[92:93], v[18:19], v[20:21]
	v_lshlrev_b32_e32 v14, 16, v94
	v_and_b32_e32 v15, 0xffff0000, v94
	v_lshlrev_b32_e32 v16, 16, v96
	v_and_b32_e32 v17, 0xffff0000, v96
	v_lshlrev_b32_e32 v18, 16, v95
	v_and_b32_e32 v19, 0xffff0000, v95
	v_lshlrev_b32_e32 v20, 16, v97
	v_and_b32_e32 v21, 0xffff0000, v97
	v_pk_add_f32 v[94:95], v[14:15], v[16:17]
	v_pk_add_f32 v[96:97], v[18:19], v[20:21]
	v_lshlrev_b32_e32 v14, 16, v98
	v_and_b32_e32 v15, 0xffff0000, v98
	v_lshlrev_b32_e32 v16, 16, v100
	v_and_b32_e32 v17, 0xffff0000, v100
	v_lshlrev_b32_e32 v18, 16, v99
	v_and_b32_e32 v19, 0xffff0000, v99
	v_lshlrev_b32_e32 v20, 16, v101
	v_and_b32_e32 v21, 0xffff0000, v101
	v_pk_add_f32 v[98:99], v[14:15], v[16:17]
	v_pk_add_f32 v[100:101], v[18:19], v[20:21]
	v_pk_mul_f32 v[12:13], v[86:87], v[86:87]
	v_pk_fma_f32 v[12:13], v[88:89], v[88:89], v[12:13]
	v_pk_fma_f32 v[12:13], v[90:91], v[90:91], v[12:13]
	v_pk_fma_f32 v[12:13], v[92:93], v[92:93], v[12:13]
	v_pk_fma_f32 v[12:13], v[94:95], v[94:95], v[12:13]
	v_pk_fma_f32 v[12:13], v[96:97], v[96:97], v[12:13]
	v_pk_fma_f32 v[12:13], v[98:99], v[98:99], v[12:13]
	v_pk_fma_f32 v[12:13], v[100:101], v[100:101], v[12:13]
	v_add_f32_e32 v5, v12, v13
	s_nop 1
	v_add_f32_dpp v5, v5, v5 quad_perm:[1,0,3,2] row_mask:0xf bank_mask:0xf
	s_nop 1
	v_add_f32_dpp v5, v5, v5 quad_perm:[2,3,0,1] row_mask:0xf bank_mask:0xf
	s_nop 1
	v_add_f32_dpp v5, v5, v5 row_half_mirror row_mask:0xf bank_mask:0xf
	s_nop 1
	v_add_f32_dpp v5, v5, v5 row_mirror row_mask:0xf bank_mask:0xf
	s_nop 1
	v_add_f32_dpp v5, v5, v5 row_bcast:15 row_mask:0xa bank_mask:0xf
	s_nop 1
	v_add_f32_dpp v5, v5, v5 row_bcast:31 row_mask:0xc bank_mask:0xf
	s_nop 1
	v_readlane_b32 s32, v5, 63
	s_nop 1
	v_mov_b32_e32 v6, s32
	v_fmamk_f32 v6, v6, 0x3a800000, v146
	v_rsq_f32_e32 v6, v6
	s_nop 0
	v_mul_f32_e32 v8, 0.5, v6
	v_pk_mul_f32 v[14:15], v[86:87], v[8:9] op_sel_hi:[1,0]
	v_pk_fma_f32 v[70:71], v[22:23], v[14:15], v[70:71]
	v_pk_mul_f32 v[14:15], v[88:89], v[8:9] op_sel_hi:[1,0]
	v_pk_fma_f32 v[72:73], v[24:25], v[14:15], v[72:73]
	v_pk_mul_f32 v[14:15], v[90:91], v[8:9] op_sel_hi:[1,0]
	v_pk_fma_f32 v[74:75], v[26:27], v[14:15], v[74:75]
	v_pk_mul_f32 v[14:15], v[92:93], v[8:9] op_sel_hi:[1,0]
	v_pk_fma_f32 v[76:77], v[28:29], v[14:15], v[76:77]
	v_pk_mul_f32 v[14:15], v[94:95], v[8:9] op_sel_hi:[1,0]
	v_pk_fma_f32 v[78:79], v[30:31], v[14:15], v[78:79]
	v_pk_mul_f32 v[14:15], v[96:97], v[8:9] op_sel_hi:[1,0]
	v_pk_fma_f32 v[80:81], v[32:33], v[14:15], v[80:81]
	v_pk_mul_f32 v[14:15], v[98:99], v[8:9] op_sel_hi:[1,0]
	v_pk_fma_f32 v[82:83], v[34:35], v[14:15], v[82:83]
	v_pk_mul_f32 v[14:15], v[100:101], v[8:9] op_sel_hi:[1,0]
	v_pk_fma_f32 v[84:85], v[36:37], v[14:15], v[84:85]
	v_pk_mul_f32 v[12:13], v[70:71], v[70:71]
	v_pk_fma_f32 v[12:13], v[72:73], v[72:73], v[12:13]
	v_pk_fma_f32 v[12:13], v[74:75], v[74:75], v[12:13]
	v_pk_fma_f32 v[12:13], v[76:77], v[76:77], v[12:13]
	v_pk_fma_f32 v[12:13], v[78:79], v[78:79], v[12:13]
	v_pk_fma_f32 v[12:13], v[80:81], v[80:81], v[12:13]
	v_pk_fma_f32 v[12:13], v[82:83], v[82:83], v[12:13]
	v_pk_fma_f32 v[12:13], v[84:85], v[84:85], v[12:13]
	v_add_f32_e32 v5, v12, v13
	s_nop 1
	v_add_f32_dpp v5, v5, v5 quad_perm:[1,0,3,2] row_mask:0xf bank_mask:0xf
	s_nop 1
	v_add_f32_dpp v5, v5, v5 quad_perm:[2,3,0,1] row_mask:0xf bank_mask:0xf
	s_nop 1
	v_add_f32_dpp v5, v5, v5 row_half_mirror row_mask:0xf bank_mask:0xf
	s_nop 1
	v_add_f32_dpp v5, v5, v5 row_mirror row_mask:0xf bank_mask:0xf
	s_nop 1
	v_add_f32_dpp v5, v5, v5 row_bcast:15 row_mask:0xa bank_mask:0xf
	s_nop 1
	v_add_f32_dpp v5, v5, v5 row_bcast:31 row_mask:0xc bank_mask:0xf
	s_nop 1
	v_readlane_b32 s32, v5, 63
	s_nop 1
	v_mov_b32_e32 v6, s32
	v_fmamk_f32 v6, v6, 0x3a800000, v146
	v_rsq_f32_e32 v6, v6
	s_nop 0
	v_mov_b32_e32 v10, v6
	v_pk_mul_f32 v[14:15], v[70:71], v[10:11] op_sel_hi:[1,0]
	v_pk_fma_f32 v[16:17], v[54:55], v[14:15], v[38:39]
	v_pk_mul_f32 v[14:15], v[72:73], v[10:11] op_sel_hi:[1,0]
	v_pk_fma_f32 v[18:19], v[56:57], v[14:15], v[40:41]
	v_cvt_pk_bf16_f32 v86, v16, v17
	v_cvt_pk_bf16_f32 v87, v18, v19
	v_pk_mul_f32 v[14:15], v[74:75], v[10:11] op_sel_hi:[1,0]
	v_pk_fma_f32 v[16:17], v[58:59], v[14:15], v[42:43]
	v_pk_mul_f32 v[14:15], v[76:77], v[10:11] op_sel_hi:[1,0]
	v_pk_fma_f32 v[18:19], v[60:61], v[14:15], v[44:45]
	v_cvt_pk_bf16_f32 v90, v16, v17
	v_cvt_pk_bf16_f32 v91, v18, v19
	v_pk_mul_f32 v[14:15], v[78:79], v[10:11] op_sel_hi:[1,0]
	v_pk_fma_f32 v[16:17], v[62:63], v[14:15], v[46:47]
	v_pk_mul_f32 v[14:15], v[80:81], v[10:11] op_sel_hi:[1,0]
	v_pk_fma_f32 v[18:19], v[64:65], v[14:15], v[48:49]
	v_cvt_pk_bf16_f32 v94, v16, v17
	v_cvt_pk_bf16_f32 v95, v18, v19
	v_pk_mul_f32 v[14:15], v[82:83], v[10:11] op_sel_hi:[1,0]
	v_pk_fma_f32 v[16:17], v[66:67], v[14:15], v[50:51]
	v_pk_mul_f32 v[14:15], v[84:85], v[10:11] op_sel_hi:[1,0]
	v_pk_fma_f32 v[18:19], v[68:69], v[14:15], v[52:53]
	v_cvt_pk_bf16_f32 v98, v16, v17
	v_cvt_pk_bf16_f32 v99, v18, v19
	global_store_dwordx2 v1, v[86:87], s[62:63] offset:0 sc1
	global_store_dwordx2 v1, v[90:91], s[62:63] offset:512 sc1
	global_store_dwordx2 v1, v[94:95], s[62:63] offset:1024 sc1
	global_store_dwordx2 v1, v[98:99], s[62:63] offset:1536 sc1
	global_store_dwordx4 v0, v[70:73], s[46:47] offset:0
	global_store_dwordx4 v0, v[74:77], s[46:47] offset:1024
	global_store_dwordx4 v0, v[78:81], s[46:47] offset:2048
	global_store_dwordx4 v0, v[82:85], s[46:47] offset:3072
	s_add_u32 s46, s46, 0x1000
	s_addc_u32 s47, s47, 0
	s_add_u32 s62, s62, 0x800
	s_addc_u32 s63, s63, 0
	s_waitcnt vmcnt(24)
	v_lshlrev_b32_e32 v14, 16, v118
	v_and_b32_e32 v15, 0xffff0000, v118
	v_lshlrev_b32_e32 v16, 16, v120
	v_and_b32_e32 v17, 0xffff0000, v120
	v_lshlrev_b32_e32 v18, 16, v119
	v_and_b32_e32 v19, 0xffff0000, v119
	v_lshlrev_b32_e32 v20, 16, v121
	v_and_b32_e32 v21, 0xffff0000, v121
	v_pk_add_f32 v[118:119], v[14:15], v[16:17]
	v_pk_add_f32 v[120:121], v[18:19], v[20:21]
	v_lshlrev_b32_e32 v14, 16, v122
	v_and_b32_e32 v15, 0xffff0000, v122
	v_lshlrev_b32_e32 v16, 16, v124
	v_and_b32_e32 v17, 0xffff0000, v124
	v_lshlrev_b32_e32 v18, 16, v123
	v_and_b32_e32 v19, 0xffff0000, v123
	v_lshlrev_b32_e32 v20, 16, v125
	v_and_b32_e32 v21, 0xffff0000, v125
	v_pk_add_f32 v[122:123], v[14:15], v[16:17]
	v_pk_add_f32 v[124:125], v[18:19], v[20:21]
	v_lshlrev_b32_e32 v14, 16, v134
	v_and_b32_e32 v15, 0xffff0000, v134
	v_lshlrev_b32_e32 v16, 16, v136
	v_and_b32_e32 v17, 0xffff0000, v136
	v_lshlrev_b32_e32 v18, 16, v135
	v_and_b32_e32 v19, 0xffff0000, v135
	v_lshlrev_b32_e32 v20, 16, v137
	v_and_b32_e32 v21, 0xffff0000, v137
	v_pk_add_f32 v[134:135], v[14:15], v[16:17]
	v_pk_add_f32 v[136:137], v[18:19], v[20:21]
	v_lshlrev_b32_e32 v14, 16, v138
	v_and_b32_e32 v15, 0xffff0000, v138
	v_lshlrev_b32_e32 v16, 16, v140
	v_and_b32_e32 v17, 0xffff0000, v140
	v_lshlrev_b32_e32 v18, 16, v139
	v_and_b32_e32 v19, 0xffff0000, v139
	v_lshlrev_b32_e32 v20, 16, v141
	v_and_b32_e32 v21, 0xffff0000, v141
	v_pk_add_f32 v[138:139], v[14:15], v[16:17]
	v_pk_add_f32 v[140:141], v[18:19], v[20:21]
	v_pk_mul_f32 v[12:13], v[118:119], v[118:119]
	v_pk_fma_f32 v[12:13], v[120:121], v[120:121], v[12:13]
	v_pk_fma_f32 v[12:13], v[122:123], v[122:123], v[12:13]
	v_pk_fma_f32 v[12:13], v[124:125], v[124:125], v[12:13]
	v_pk_fma_f32 v[12:13], v[134:135], v[134:135], v[12:13]
	v_pk_fma_f32 v[12:13], v[136:137], v[136:137], v[12:13]
	v_pk_fma_f32 v[12:13], v[138:139], v[138:139], v[12:13]
	v_pk_fma_f32 v[12:13], v[140:141], v[140:141], v[12:13]
	v_add_f32_e32 v5, v12, v13
	s_nop 1
	v_add_f32_dpp v5, v5, v5 quad_perm:[1,0,3,2] row_mask:0xf bank_mask:0xf
	s_nop 1
	v_add_f32_dpp v5, v5, v5 quad_perm:[2,3,0,1] row_mask:0xf bank_mask:0xf
	s_nop 1
	v_add_f32_dpp v5, v5, v5 row_half_mirror row_mask:0xf bank_mask:0xf
	s_nop 1
	v_add_f32_dpp v5, v5, v5 row_mirror row_mask:0xf bank_mask:0xf
	s_nop 1
	v_add_f32_dpp v5, v5, v5 row_bcast:15 row_mask:0xa bank_mask:0xf
	s_nop 1
	v_add_f32_dpp v5, v5, v5 row_bcast:31 row_mask:0xc bank_mask:0xf
	s_nop 1
	v_readlane_b32 s32, v5, 63
	s_nop 1
	v_mov_b32_e32 v6, s32
	v_fmamk_f32 v6, v6, 0x3a800000, v146
	v_rsq_f32_e32 v6, v6
	s_nop 0
	v_mul_f32_e32 v8, 0.5, v6
	v_pk_mul_f32 v[14:15], v[118:119], v[8:9] op_sel_hi:[1,0]
	v_pk_fma_f32 v[102:103], v[22:23], v[14:15], v[102:103]
	v_pk_mul_f32 v[14:15], v[120:121], v[8:9] op_sel_hi:[1,0]
	v_pk_fma_f32 v[104:105], v[24:25], v[14:15], v[104:105]
	v_pk_mul_f32 v[14:15], v[122:123], v[8:9] op_sel_hi:[1,0]
	v_pk_fma_f32 v[106:107], v[26:27], v[14:15], v[106:107]
	v_pk_mul_f32 v[14:15], v[124:125], v[8:9] op_sel_hi:[1,0]
	v_pk_fma_f32 v[108:109], v[28:29], v[14:15], v[108:109]
	v_pk_mul_f32 v[14:15], v[134:135], v[8:9] op_sel_hi:[1,0]
	v_pk_fma_f32 v[110:111], v[30:31], v[14:15], v[110:111]
	v_pk_mul_f32 v[14:15], v[136:137], v[8:9] op_sel_hi:[1,0]
	v_pk_fma_f32 v[112:113], v[32:33], v[14:15], v[112:113]
	v_pk_mul_f32 v[14:15], v[138:139], v[8:9] op_sel_hi:[1,0]
	v_pk_fma_f32 v[114:115], v[34:35], v[14:15], v[114:115]
	v_pk_mul_f32 v[14:15], v[140:141], v[8:9] op_sel_hi:[1,0]
	v_pk_fma_f32 v[116:117], v[36:37], v[14:15], v[116:117]
	v_pk_mul_f32 v[12:13], v[102:103], v[102:103]
	v_pk_fma_f32 v[12:13], v[104:105], v[104:105], v[12:13]
	v_pk_fma_f32 v[12:13], v[106:107], v[106:107], v[12:13]
	v_pk_fma_f32 v[12:13], v[108:109], v[108:109], v[12:13]
	v_pk_fma_f32 v[12:13], v[110:111], v[110:111], v[12:13]
	v_pk_fma_f32 v[12:13], v[112:113], v[112:113], v[12:13]
	v_pk_fma_f32 v[12:13], v[114:115], v[114:115], v[12:13]
	v_pk_fma_f32 v[12:13], v[116:117], v[116:117], v[12:13]
	v_add_f32_e32 v5, v12, v13
	s_nop 1
	v_add_f32_dpp v5, v5, v5 quad_perm:[1,0,3,2] row_mask:0xf bank_mask:0xf
	s_nop 1
	v_add_f32_dpp v5, v5, v5 quad_perm:[2,3,0,1] row_mask:0xf bank_mask:0xf
	s_nop 1
	v_add_f32_dpp v5, v5, v5 row_half_mirror row_mask:0xf bank_mask:0xf
	s_nop 1
	v_add_f32_dpp v5, v5, v5 row_mirror row_mask:0xf bank_mask:0xf
	s_nop 1
	v_add_f32_dpp v5, v5, v5 row_bcast:15 row_mask:0xa bank_mask:0xf
	s_nop 1
	v_add_f32_dpp v5, v5, v5 row_bcast:31 row_mask:0xc bank_mask:0xf
	s_nop 1
	v_readlane_b32 s32, v5, 63
	s_nop 1
	v_mov_b32_e32 v6, s32
	v_fmamk_f32 v6, v6, 0x3a800000, v146
	v_rsq_f32_e32 v6, v6
	s_nop 0
	v_mov_b32_e32 v10, v6
	v_pk_mul_f32 v[14:15], v[102:103], v[10:11] op_sel_hi:[1,0]
	v_pk_fma_f32 v[16:17], v[54:55], v[14:15], v[38:39]
	v_pk_mul_f32 v[14:15], v[104:105], v[10:11] op_sel_hi:[1,0]
	v_pk_fma_f32 v[18:19], v[56:57], v[14:15], v[40:41]
	v_cvt_pk_bf16_f32 v118, v16, v17
	v_cvt_pk_bf16_f32 v119, v18, v19
	v_pk_mul_f32 v[14:15], v[106:107], v[10:11] op_sel_hi:[1,0]
	v_pk_fma_f32 v[16:17], v[58:59], v[14:15], v[42:43]
	v_pk_mul_f32 v[14:15], v[108:109], v[10:11] op_sel_hi:[1,0]
	v_pk_fma_f32 v[18:19], v[60:61], v[14:15], v[44:45]
	v_cvt_pk_bf16_f32 v122, v16, v17
	v_cvt_pk_bf16_f32 v123, v18, v19
	v_pk_mul_f32 v[14:15], v[110:111], v[10:11] op_sel_hi:[1,0]
	v_pk_fma_f32 v[16:17], v[62:63], v[14:15], v[46:47]
	v_pk_mul_f32 v[14:15], v[112:113], v[10:11] op_sel_hi:[1,0]
	v_pk_fma_f32 v[18:19], v[64:65], v[14:15], v[48:49]
	v_cvt_pk_bf16_f32 v134, v16, v17
	v_cvt_pk_bf16_f32 v135, v18, v19
	v_pk_mul_f32 v[14:15], v[114:115], v[10:11] op_sel_hi:[1,0]
	v_pk_fma_f32 v[16:17], v[66:67], v[14:15], v[50:51]
	v_pk_mul_f32 v[14:15], v[116:117], v[10:11] op_sel_hi:[1,0]
	v_pk_fma_f32 v[18:19], v[68:69], v[14:15], v[52:53]
	v_cvt_pk_bf16_f32 v138, v16, v17
	v_cvt_pk_bf16_f32 v139, v18, v19
	global_store_dwordx2 v1, v[118:119], s[62:63] offset:0 sc1
	global_store_dwordx2 v1, v[122:123], s[62:63] offset:512 sc1
	global_store_dwordx2 v1, v[134:135], s[62:63] offset:1024 sc1
	global_store_dwordx2 v1, v[138:139], s[62:63] offset:1536 sc1
	global_store_dwordx4 v0, v[102:105], s[46:47] offset:0
	global_store_dwordx4 v0, v[106:109], s[46:47] offset:1024
	global_store_dwordx4 v0, v[110:113], s[46:47] offset:2048
	global_store_dwordx4 v0, v[114:117], s[46:47] offset:3072
	s_add_u32 s46, s46, 0x1000
	s_addc_u32 s47, s47, 0
	s_add_u32 s62, s62, 0x800
	s_addc_u32 s63, s63, 0
	s_waitcnt vmcnt(24)
	v_lshlrev_b32_e32 v14, 16, v172
	v_and_b32_e32 v15, 0xffff0000, v172
	v_lshlrev_b32_e32 v16, 16, v174
	v_and_b32_e32 v17, 0xffff0000, v174
	v_lshlrev_b32_e32 v18, 16, v173
	v_and_b32_e32 v19, 0xffff0000, v173
	v_lshlrev_b32_e32 v20, 16, v175
	v_and_b32_e32 v21, 0xffff0000, v175
	v_pk_add_f32 v[172:173], v[14:15], v[16:17]
	v_pk_add_f32 v[174:175], v[18:19], v[20:21]
	v_lshlrev_b32_e32 v14, 16, v176
	v_and_b32_e32 v15, 0xffff0000, v176
	v_lshlrev_b32_e32 v16, 16, v178
	v_and_b32_e32 v17, 0xffff0000, v178
	v_lshlrev_b32_e32 v18, 16, v177
	v_and_b32_e32 v19, 0xffff0000, v177
	v_lshlrev_b32_e32 v20, 16, v179
	v_and_b32_e32 v21, 0xffff0000, v179
	v_pk_add_f32 v[176:177], v[14:15], v[16:17]
	v_pk_add_f32 v[178:179], v[18:19], v[20:21]
	v_lshlrev_b32_e32 v14, 16, v204
	v_and_b32_e32 v15, 0xffff0000, v204
	v_lshlrev_b32_e32 v16, 16, v206
	v_and_b32_e32 v17, 0xffff0000, v206
	v_lshlrev_b32_e32 v18, 16, v205
	v_and_b32_e32 v19, 0xffff0000, v205
	v_lshlrev_b32_e32 v20, 16, v207
	v_and_b32_e32 v21, 0xffff0000, v207
	v_pk_add_f32 v[204:205], v[14:15], v[16:17]
	v_pk_add_f32 v[206:207], v[18:19], v[20:21]
	v_lshlrev_b32_e32 v14, 16, v214
	v_and_b32_e32 v15, 0xffff0000, v214
	v_lshlrev_b32_e32 v16, 16, v216
	v_and_b32_e32 v17, 0xffff0000, v216
	v_lshlrev_b32_e32 v18, 16, v215
	v_and_b32_e32 v19, 0xffff0000, v215
	v_lshlrev_b32_e32 v20, 16, v217
	v_and_b32_e32 v21, 0xffff0000, v217
	v_pk_add_f32 v[214:215], v[14:15], v[16:17]
	v_pk_add_f32 v[216:217], v[18:19], v[20:21]
	v_pk_mul_f32 v[12:13], v[172:173], v[172:173]
	v_pk_fma_f32 v[12:13], v[174:175], v[174:175], v[12:13]
	v_pk_fma_f32 v[12:13], v[176:177], v[176:177], v[12:13]
	v_pk_fma_f32 v[12:13], v[178:179], v[178:179], v[12:13]
	v_pk_fma_f32 v[12:13], v[204:205], v[204:205], v[12:13]
	v_pk_fma_f32 v[12:13], v[206:207], v[206:207], v[12:13]
	v_pk_fma_f32 v[12:13], v[214:215], v[214:215], v[12:13]
	v_pk_fma_f32 v[12:13], v[216:217], v[216:217], v[12:13]
	v_add_f32_e32 v5, v12, v13
	s_nop 1
	v_add_f32_dpp v5, v5, v5 quad_perm:[1,0,3,2] row_mask:0xf bank_mask:0xf
	s_nop 1
	v_add_f32_dpp v5, v5, v5 quad_perm:[2,3,0,1] row_mask:0xf bank_mask:0xf
	s_nop 1
	v_add_f32_dpp v5, v5, v5 row_half_mirror row_mask:0xf bank_mask:0xf
	s_nop 1
	v_add_f32_dpp v5, v5, v5 row_mirror row_mask:0xf bank_mask:0xf
	s_nop 1
	v_add_f32_dpp v5, v5, v5 row_bcast:15 row_mask:0xa bank_mask:0xf
	s_nop 1
	v_add_f32_dpp v5, v5, v5 row_bcast:31 row_mask:0xc bank_mask:0xf
	s_nop 1
	v_readlane_b32 s32, v5, 63
	s_nop 1
	v_mov_b32_e32 v6, s32
	v_fmamk_f32 v6, v6, 0x3a800000, v146
	v_rsq_f32_e32 v6, v6
	s_nop 0
	v_mul_f32_e32 v8, 0.5, v6
	v_pk_mul_f32 v[14:15], v[172:173], v[8:9] op_sel_hi:[1,0]
	v_pk_fma_f32 v[154:155], v[22:23], v[14:15], v[154:155]
	v_pk_mul_f32 v[14:15], v[174:175], v[8:9] op_sel_hi:[1,0]
	v_pk_fma_f32 v[156:157], v[24:25], v[14:15], v[156:157]
	v_pk_mul_f32 v[14:15], v[176:177], v[8:9] op_sel_hi:[1,0]
	v_pk_fma_f32 v[158:159], v[26:27], v[14:15], v[158:159]
	v_pk_mul_f32 v[14:15], v[178:179], v[8:9] op_sel_hi:[1,0]
	v_pk_fma_f32 v[160:161], v[28:29], v[14:15], v[160:161]
	v_pk_mul_f32 v[14:15], v[204:205], v[8:9] op_sel_hi:[1,0]
	v_pk_fma_f32 v[162:163], v[30:31], v[14:15], v[162:163]
	v_pk_mul_f32 v[14:15], v[206:207], v[8:9] op_sel_hi:[1,0]
	v_pk_fma_f32 v[164:165], v[32:33], v[14:15], v[164:165]
	v_pk_mul_f32 v[14:15], v[214:215], v[8:9] op_sel_hi:[1,0]
	v_pk_fma_f32 v[168:169], v[34:35], v[14:15], v[168:169]
	v_pk_mul_f32 v[14:15], v[216:217], v[8:9] op_sel_hi:[1,0]
	v_pk_fma_f32 v[170:171], v[36:37], v[14:15], v[170:171]
	v_pk_mul_f32 v[12:13], v[154:155], v[154:155]
	v_pk_fma_f32 v[12:13], v[156:157], v[156:157], v[12:13]
	v_pk_fma_f32 v[12:13], v[158:159], v[158:159], v[12:13]
	v_pk_fma_f32 v[12:13], v[160:161], v[160:161], v[12:13]
	v_pk_fma_f32 v[12:13], v[162:163], v[162:163], v[12:13]
	v_pk_fma_f32 v[12:13], v[164:165], v[164:165], v[12:13]
	v_pk_fma_f32 v[12:13], v[168:169], v[168:169], v[12:13]
	v_pk_fma_f32 v[12:13], v[170:171], v[170:171], v[12:13]
	v_add_f32_e32 v5, v12, v13
	s_nop 1
	v_add_f32_dpp v5, v5, v5 quad_perm:[1,0,3,2] row_mask:0xf bank_mask:0xf
	s_nop 1
	v_add_f32_dpp v5, v5, v5 quad_perm:[2,3,0,1] row_mask:0xf bank_mask:0xf
	s_nop 1
	v_add_f32_dpp v5, v5, v5 row_half_mirror row_mask:0xf bank_mask:0xf
	s_nop 1
	v_add_f32_dpp v5, v5, v5 row_mirror row_mask:0xf bank_mask:0xf
	s_nop 1
	v_add_f32_dpp v5, v5, v5 row_bcast:15 row_mask:0xa bank_mask:0xf
	s_nop 1
	v_add_f32_dpp v5, v5, v5 row_bcast:31 row_mask:0xc bank_mask:0xf
	s_nop 1
	v_readlane_b32 s32, v5, 63
	s_nop 1
	v_mov_b32_e32 v6, s32
	v_fmamk_f32 v6, v6, 0x3a800000, v146
	v_rsq_f32_e32 v6, v6
	s_nop 0
	v_mov_b32_e32 v10, v6
	v_pk_mul_f32 v[14:15], v[154:155], v[10:11] op_sel_hi:[1,0]
	v_pk_fma_f32 v[16:17], v[54:55], v[14:15], v[38:39]
	v_pk_mul_f32 v[14:15], v[156:157], v[10:11] op_sel_hi:[1,0]
	v_pk_fma_f32 v[18:19], v[56:57], v[14:15], v[40:41]
	v_cvt_pk_bf16_f32 v172, v16, v17
	v_cvt_pk_bf16_f32 v173, v18, v19
	v_pk_mul_f32 v[14:15], v[158:159], v[10:11] op_sel_hi:[1,0]
	v_pk_fma_f32 v[16:17], v[58:59], v[14:15], v[42:43]
	v_pk_mul_f32 v[14:15], v[160:161], v[10:11] op_sel_hi:[1,0]
	v_pk_fma_f32 v[18:19], v[60:61], v[14:15], v[44:45]
	v_cvt_pk_bf16_f32 v176, v16, v17
	v_cvt_pk_bf16_f32 v177, v18, v19
	v_pk_mul_f32 v[14:15], v[162:163], v[10:11] op_sel_hi:[1,0]
	v_pk_fma_f32 v[16:17], v[62:63], v[14:15], v[46:47]
	v_pk_mul_f32 v[14:15], v[164:165], v[10:11] op_sel_hi:[1,0]
	v_pk_fma_f32 v[18:19], v[64:65], v[14:15], v[48:49]
	v_cvt_pk_bf16_f32 v204, v16, v17
	v_cvt_pk_bf16_f32 v205, v18, v19
	v_pk_mul_f32 v[14:15], v[168:169], v[10:11] op_sel_hi:[1,0]
	v_pk_fma_f32 v[16:17], v[66:67], v[14:15], v[50:51]
	v_pk_mul_f32 v[14:15], v[170:171], v[10:11] op_sel_hi:[1,0]
	v_pk_fma_f32 v[18:19], v[68:69], v[14:15], v[52:53]
	v_cvt_pk_bf16_f32 v214, v16, v17
	v_cvt_pk_bf16_f32 v215, v18, v19
	global_store_dwordx2 v1, v[172:173], s[62:63] offset:0 sc1
	global_store_dwordx2 v1, v[176:177], s[62:63] offset:512 sc1
	global_store_dwordx2 v1, v[204:205], s[62:63] offset:1024 sc1
	global_store_dwordx2 v1, v[214:215], s[62:63] offset:1536 sc1
	global_store_dwordx4 v0, v[154:157], s[46:47] offset:0
	global_store_dwordx4 v0, v[158:161], s[46:47] offset:1024
	global_store_dwordx4 v0, v[162:165], s[46:47] offset:2048
	global_store_dwordx4 v0, v[168:171], s[46:47] offset:3072
	s_add_u32 s46, s46, 0x1000
	s_addc_u32 s47, s47, 0
	s_add_u32 s62, s62, 0x800
	s_addc_u32 s63, s63, 0
	s_waitcnt vmcnt(24)
	v_lshlrev_b32_e32 v14, 16, v234
	v_and_b32_e32 v15, 0xffff0000, v234
	v_lshlrev_b32_e32 v16, 16, v236
	v_and_b32_e32 v17, 0xffff0000, v236
	v_lshlrev_b32_e32 v18, 16, v235
	v_and_b32_e32 v19, 0xffff0000, v235
	v_lshlrev_b32_e32 v20, 16, v237
	v_and_b32_e32 v21, 0xffff0000, v237
	v_pk_add_f32 v[234:235], v[14:15], v[16:17]
	v_pk_add_f32 v[236:237], v[18:19], v[20:21]
	v_lshlrev_b32_e32 v14, 16, v238
	v_and_b32_e32 v15, 0xffff0000, v238
	v_lshlrev_b32_e32 v16, 16, v240
	v_and_b32_e32 v17, 0xffff0000, v240
	v_lshlrev_b32_e32 v18, 16, v239
	v_and_b32_e32 v19, 0xffff0000, v239
	v_lshlrev_b32_e32 v20, 16, v241
	v_and_b32_e32 v21, 0xffff0000, v241
	v_pk_add_f32 v[238:239], v[14:15], v[16:17]
	v_pk_add_f32 v[240:241], v[18:19], v[20:21]
	v_lshlrev_b32_e32 v14, 16, v242
	v_and_b32_e32 v15, 0xffff0000, v242
	v_lshlrev_b32_e32 v16, 16, v244
	v_and_b32_e32 v17, 0xffff0000, v244
	v_lshlrev_b32_e32 v18, 16, v243
	v_and_b32_e32 v19, 0xffff0000, v243
	v_lshlrev_b32_e32 v20, 16, v245
	v_and_b32_e32 v21, 0xffff0000, v245
	v_pk_add_f32 v[242:243], v[14:15], v[16:17]
	v_pk_add_f32 v[244:245], v[18:19], v[20:21]
	v_lshlrev_b32_e32 v14, 16, v246
	v_and_b32_e32 v15, 0xffff0000, v246
	v_lshlrev_b32_e32 v16, 16, v248
	v_and_b32_e32 v17, 0xffff0000, v248
	v_lshlrev_b32_e32 v18, 16, v247
	v_and_b32_e32 v19, 0xffff0000, v247
	v_lshlrev_b32_e32 v20, 16, v249
	v_and_b32_e32 v21, 0xffff0000, v249
	v_pk_add_f32 v[246:247], v[14:15], v[16:17]
	v_pk_add_f32 v[248:249], v[18:19], v[20:21]
	v_pk_mul_f32 v[12:13], v[234:235], v[234:235]
	v_pk_fma_f32 v[12:13], v[236:237], v[236:237], v[12:13]
	v_pk_fma_f32 v[12:13], v[238:239], v[238:239], v[12:13]
	v_pk_fma_f32 v[12:13], v[240:241], v[240:241], v[12:13]
	v_pk_fma_f32 v[12:13], v[242:243], v[242:243], v[12:13]
	v_pk_fma_f32 v[12:13], v[244:245], v[244:245], v[12:13]
	v_pk_fma_f32 v[12:13], v[246:247], v[246:247], v[12:13]
	v_pk_fma_f32 v[12:13], v[248:249], v[248:249], v[12:13]
	v_add_f32_e32 v5, v12, v13
	s_nop 1
	v_add_f32_dpp v5, v5, v5 quad_perm:[1,0,3,2] row_mask:0xf bank_mask:0xf
	s_nop 1
	v_add_f32_dpp v5, v5, v5 quad_perm:[2,3,0,1] row_mask:0xf bank_mask:0xf
	s_nop 1
	v_add_f32_dpp v5, v5, v5 row_half_mirror row_mask:0xf bank_mask:0xf
	s_nop 1
	v_add_f32_dpp v5, v5, v5 row_mirror row_mask:0xf bank_mask:0xf
	s_nop 1
	v_add_f32_dpp v5, v5, v5 row_bcast:15 row_mask:0xa bank_mask:0xf
	s_nop 1
	v_add_f32_dpp v5, v5, v5 row_bcast:31 row_mask:0xc bank_mask:0xf
	s_nop 1
	v_readlane_b32 s32, v5, 63
	s_nop 1
	v_mov_b32_e32 v6, s32
	v_fmamk_f32 v6, v6, 0x3a800000, v146
	v_rsq_f32_e32 v6, v6
	s_nop 0
	v_mul_f32_e32 v8, 0.5, v6
	v_pk_mul_f32 v[14:15], v[234:235], v[8:9] op_sel_hi:[1,0]
	v_pk_fma_f32 v[218:219], v[22:23], v[14:15], v[218:219]
	v_pk_mul_f32 v[14:15], v[236:237], v[8:9] op_sel_hi:[1,0]
	v_pk_fma_f32 v[220:221], v[24:25], v[14:15], v[220:221]
	v_pk_mul_f32 v[14:15], v[238:239], v[8:9] op_sel_hi:[1,0]
	v_pk_fma_f32 v[222:223], v[26:27], v[14:15], v[222:223]
	v_pk_mul_f32 v[14:15], v[240:241], v[8:9] op_sel_hi:[1,0]
	v_pk_fma_f32 v[224:225], v[28:29], v[14:15], v[224:225]
	v_pk_mul_f32 v[14:15], v[242:243], v[8:9] op_sel_hi:[1,0]
	v_pk_fma_f32 v[226:227], v[30:31], v[14:15], v[226:227]
	v_pk_mul_f32 v[14:15], v[244:245], v[8:9] op_sel_hi:[1,0]
	v_pk_fma_f32 v[228:229], v[32:33], v[14:15], v[228:229]
	v_pk_mul_f32 v[14:15], v[246:247], v[8:9] op_sel_hi:[1,0]
	v_pk_fma_f32 v[230:231], v[34:35], v[14:15], v[230:231]
	v_pk_mul_f32 v[14:15], v[248:249], v[8:9] op_sel_hi:[1,0]
	v_pk_fma_f32 v[232:233], v[36:37], v[14:15], v[232:233]
	v_pk_mul_f32 v[12:13], v[218:219], v[218:219]
	v_pk_fma_f32 v[12:13], v[220:221], v[220:221], v[12:13]
	v_pk_fma_f32 v[12:13], v[222:223], v[222:223], v[12:13]
	v_pk_fma_f32 v[12:13], v[224:225], v[224:225], v[12:13]
	v_pk_fma_f32 v[12:13], v[226:227], v[226:227], v[12:13]
	v_pk_fma_f32 v[12:13], v[228:229], v[228:229], v[12:13]
	v_pk_fma_f32 v[12:13], v[230:231], v[230:231], v[12:13]
	v_pk_fma_f32 v[12:13], v[232:233], v[232:233], v[12:13]
	v_add_f32_e32 v5, v12, v13
	s_nop 1
	v_add_f32_dpp v5, v5, v5 quad_perm:[1,0,3,2] row_mask:0xf bank_mask:0xf
	s_nop 1
	v_add_f32_dpp v5, v5, v5 quad_perm:[2,3,0,1] row_mask:0xf bank_mask:0xf
	s_nop 1
	v_add_f32_dpp v5, v5, v5 row_half_mirror row_mask:0xf bank_mask:0xf
	s_nop 1
	v_add_f32_dpp v5, v5, v5 row_mirror row_mask:0xf bank_mask:0xf
	s_nop 1
	v_add_f32_dpp v5, v5, v5 row_bcast:15 row_mask:0xa bank_mask:0xf
	s_nop 1
	v_add_f32_dpp v5, v5, v5 row_bcast:31 row_mask:0xc bank_mask:0xf
	s_nop 1
	v_readlane_b32 s32, v5, 63
	s_nop 1
	v_mov_b32_e32 v6, s32
	v_fmamk_f32 v6, v6, 0x3a800000, v146
	v_rsq_f32_e32 v6, v6
	s_nop 0
	v_mov_b32_e32 v10, v6
	v_pk_mul_f32 v[14:15], v[218:219], v[10:11] op_sel_hi:[1,0]
	v_pk_fma_f32 v[16:17], v[54:55], v[14:15], v[38:39]
	v_pk_mul_f32 v[14:15], v[220:221], v[10:11] op_sel_hi:[1,0]
	v_pk_fma_f32 v[18:19], v[56:57], v[14:15], v[40:41]
	v_cvt_pk_bf16_f32 v234, v16, v17
	v_cvt_pk_bf16_f32 v235, v18, v19
	v_pk_mul_f32 v[14:15], v[222:223], v[10:11] op_sel_hi:[1,0]
	v_pk_fma_f32 v[16:17], v[58:59], v[14:15], v[42:43]
	v_pk_mul_f32 v[14:15], v[224:225], v[10:11] op_sel_hi:[1,0]
	v_pk_fma_f32 v[18:19], v[60:61], v[14:15], v[44:45]
	v_cvt_pk_bf16_f32 v238, v16, v17
	v_cvt_pk_bf16_f32 v239, v18, v19
	v_pk_mul_f32 v[14:15], v[226:227], v[10:11] op_sel_hi:[1,0]
	v_pk_fma_f32 v[16:17], v[62:63], v[14:15], v[46:47]
	v_pk_mul_f32 v[14:15], v[228:229], v[10:11] op_sel_hi:[1,0]
	v_pk_fma_f32 v[18:19], v[64:65], v[14:15], v[48:49]
	v_cvt_pk_bf16_f32 v242, v16, v17
	v_cvt_pk_bf16_f32 v243, v18, v19
	v_pk_mul_f32 v[14:15], v[230:231], v[10:11] op_sel_hi:[1,0]
	v_pk_fma_f32 v[16:17], v[66:67], v[14:15], v[50:51]
	v_pk_mul_f32 v[14:15], v[232:233], v[10:11] op_sel_hi:[1,0]
	v_pk_fma_f32 v[18:19], v[68:69], v[14:15], v[52:53]
	v_cvt_pk_bf16_f32 v246, v16, v17
	v_cvt_pk_bf16_f32 v247, v18, v19
	global_store_dwordx2 v1, v[234:235], s[62:63] offset:0 sc1
	global_store_dwordx2 v1, v[238:239], s[62:63] offset:512 sc1
	global_store_dwordx2 v1, v[242:243], s[62:63] offset:1024 sc1
	global_store_dwordx2 v1, v[246:247], s[62:63] offset:1536 sc1
	global_store_dwordx4 v0, v[218:221], s[46:47] offset:0
	global_store_dwordx4 v0, v[222:225], s[46:47] offset:1024
	global_store_dwordx4 v0, v[226:229], s[46:47] offset:2048
	global_store_dwordx4 v0, v[230:233], s[46:47] offset:3072
	s_add_u32 s46, s46, 0x1000
	s_addc_u32 s47, s47, 0
	s_add_u32 s62, s62, 0x800
	s_addc_u32 s63, s63, 0
.LBB0_523:
	s_or_b64 exec, exec, s[8:9]
	s_waitcnt vmcnt(0)
	v_mov_b32_e32 v0, v147
	s_barrier
	s_nop 0
	v_readfirstlane_b32 vcc_lo, v0
	s_nop 1
	s_cmp_eq_u32 vcc_lo, 64
	s_cbranch_scc0 .Lxb_noinv_4
	buffer_inv sc1
.Lxb_noinv_4:
	v_cmp_eq_u32_e32 vcc, 0, v0
	s_and_saveexec_b64 s[4:5], vcc
	s_cbranch_execz .LBB0_575
	s_load_dwordx2 s[12:13], s[16:17], 0x98
	v_readlane_b32 s14, v255, 0
	v_readlane_b32 s15, v255, 47
	s_nop 0
	s_lshr_b32 s24, s14, 3
	s_and_b32 s24, s24, 7
	s_and_b32 s27, s14, 6
	s_lshl_b32 s27, s27, 2
	s_or_b32 s27, s27, s24
	s_and_b32 s30, s14, 3
	s_lshl_b32 s30, s30, 3
	s_or_b32 s30, s30, s24
	s_lshl_b32 s27, s27, 7
	s_add_u32 s27, s27, 0xb000
	s_add_u32 s15, s15, 8
	v_writelane_b32 v255, s15, 47
	v_mov_b32_e32 v0, s27
	s_waitcnt lgkmcnt(0)
	global_atomic_add v0, v189, s[12:13]
	v_writelane_b32 v255, s27, 50
	v_writelane_b32 v255, s15, 51
	v_writelane_b32 v255, s27, 52
	v_writelane_b32 v255, s15, 53
	v_writelane_b32 v255, s12, 54
	v_writelane_b32 v255, s13, 55

.Lgw_skip_mi:
	s_or_b64 exec, exec, s[100:101]
	s_waitcnt vmcnt(4)
	s_barrier
	s_mov_b32 m0, s87
	s_add_u32 s18, s4, 0x40000
	global_load_lds_dwordx4 v132, s[4:5]
	s_mov_b32 m0, s76
	s_addc_u32 s19, s5, 0
	s_add_i32 s77, s87, 0x4000
	global_load_lds_dwordx4 v136, s[4:5]
	s_mov_b32 m0, s77
	s_add_i32 s74, s87, 0x6000
	global_load_lds_dwordx4 v132, s[18:19]
	s_mov_b32 m0, s74
	v_mov_b32_e32 v135, v145
	global_load_lds_dwordx4 v136, s[18:19]
	v_mov_b32_e32 v139, v145
	v_mov_b32_e32 v133, v145
	v_mov_b32_e32 v137, v145
	s_cmp_eq_u32 s10, 1
	v_lshl_add_u64 v[6:7], s[42:43], 0, v[134:135]
	v_lshl_add_u64 v[4:5], s[42:43], 0, v[138:139]
	v_lshl_add_u64 v[0:1], s[4:5], 0, v[132:133]
	s_cselect_b64 s[18:19], -1, 0
	s_cmp_lg_u32 s10, 1
	v_lshl_add_u64 v[2:3], s[4:5], 0, v[136:137]
	s_cbranch_scc1 .LBB0_584
	s_barrier

.LBB0_1169:
	s_waitcnt vmcnt(0)
	v_mov_b32_e32 v0, v147
	s_waitcnt vmcnt(0)
	s_barrier
	s_nop 0
	v_readfirstlane_b32 vcc_lo, v0
	s_nop 1
	s_cmp_eq_u32 vcc_lo, 64
	s_cbranch_scc0 .Lxb_noinv_7
	buffer_inv sc1
.Lxb_noinv_7:
	v_cmp_eq_u32_e32 vcc, 0, v0
	s_and_saveexec_b64 s[4:5], vcc
	s_xor_b64 s[4:5], exec, s[4:5]
	s_cbranch_execz .LBB0_1222
	s_load_dwordx2 s[12:13], s[8:9], 0x98
	v_readlane_b32 s14, v255, 0
	v_readlane_b32 s15, v255, 46
	s_nop 0
	s_lshr_b32 s24, s14, 3
	s_and_b32 s24, s24, 7
	s_and_b32 s27, s14, 6
	s_lshl_b32 s27, s27, 2
	s_or_b32 s27, s27, s24
	s_and_b32 s30, s14, 3
	s_lshl_b32 s30, s30, 3
	s_or_b32 s30, s30, s24
	s_lshl_b32 s27, s27, 7
	s_add_u32 s27, s27, 0xa000
	s_lshl_b32 s30, s30, 7
	s_add_u32 s30, s30, 0xa000
	s_add_u32 s15, s15, 8
	v_writelane_b32 v255, s15, 46
	v_mov_b32_e32 v0, s30
	s_waitcnt lgkmcnt(0)
	global_atomic_add v0, v189, s[12:13]

.Lnw_skip_n2:
	s_or_b64 exec, exec, s[40:41]
	s_waitcnt vmcnt(36)
	s_barrier
	global_load_dwordx2 v[86:87], v1, s[58:59] offset:0
	global_load_dwordx2 v[90:91], v1, s[58:59] offset:512
	global_load_dwordx2 v[94:95], v1, s[58:59] offset:1024
	global_load_dwordx2 v[98:99], v1, s[58:59] offset:1536
	global_load_dwordx2 v[88:89], v1, s[60:61] offset:0
	global_load_dwordx2 v[92:93], v1, s[60:61] offset:512
	global_load_dwordx2 v[96:97], v1, s[60:61] offset:1024
	global_load_dwordx2 v[100:101], v1, s[60:61] offset:1536
	s_add_u32 s58, s58, 0x800
	s_addc_u32 s59, s59, 0
	s_add_u32 s60, s60, 0x800
	s_addc_u32 s61, s61, 0
	global_load_dwordx2 v[118:119], v1, s[58:59] offset:0
	global_load_dwordx2 v[122:123], v1, s[58:59] offset:512
	global_load_dwordx2 v[134:135], v1, s[58:59] offset:1024
	global_load_dwordx2 v[138:139], v1, s[58:59] offset:1536
	global_load_dwordx2 v[120:121], v1, s[60:61] offset:0
	global_load_dwordx2 v[124:125], v1, s[60:61] offset:512
	global_load_dwordx2 v[136:137], v1, s[60:61] offset:1024
	global_load_dwordx2 v[140:141], v1, s[60:61] offset:1536
	s_add_u32 s58, s58, 0x800
	s_addc_u32 s59, s59, 0
	s_add_u32 s60, s60, 0x800
	s_addc_u32 s61, s61, 0
	global_load_dwordx2 v[172:173], v1, s[58:59] offset:0
	global_load_dwordx2 v[176:177], v1, s[58:59] offset:512
	global_load_dwordx2 v[204:205], v1, s[58:59] offset:1024
	global_load_dwordx2 v[214:215], v1, s[58:59] offset:1536
	global_load_dwordx2 v[174:175], v1, s[60:61] offset:0
	global_load_dwordx2 v[178:179], v1, s[60:61] offset:512
	global_load_dwordx2 v[206:207], v1, s[60:61] offset:1024
	global_load_dwordx2 v[216:217], v1, s[60:61] offset:1536
	s_add_u32 s58, s58, 0x800
	s_addc_u32 s59, s59, 0
	s_add_u32 s60, s60, 0x800
	s_addc_u32 s61, s61, 0
	global_load_dwordx2 v[234:235], v1, s[58:59] offset:0
	global_load_dwordx2 v[238:239], v1, s[58:59] offset:512
	global_load_dwordx2 v[242:243], v1, s[58:59] offset:1024
	global_load_dwordx2 v[246:247], v1, s[58:59] offset:1536
	global_load_dwordx2 v[236:237], v1, s[60:61] offset:0
	global_load_dwordx2 v[240:241], v1, s[60:61] offset:512
	global_load_dwordx2 v[244:245], v1, s[60:61] offset:1024
	global_load_dwordx2 v[248:249], v1, s[60:61] offset:1536
	s_add_u32 s58, s58, 0x800
	s_addc_u32 s59, s59, 0
	s_add_u32 s60, s60, 0x800
	s_addc_u32 s61, s61, 0
	s_waitcnt vmcnt(24)
	v_lshlrev_b32_e32 v14, 16, v86
	v_and_b32_e32 v15, 0xffff0000, v86
	v_lshlrev_b32_e32 v16, 16, v88
	v_and_b32_e32 v17, 0xffff0000, v88
	v_lshlrev_b32_e32 v18, 16, v87
	v_and_b32_e32 v19, 0xffff0000, v87
	v_lshlrev_b32_e32 v20, 16, v89
	v_and_b32_e32 v21, 0xffff0000, v89
	v_pk_add_f32 v[86:87], v[14:15], v[16:17]
	v_pk_add_f32 v[88:89], v[18:19], v[20:21]
	v_lshlrev_b32_e32 v14, 16, v90
	v_and_b32_e32 v15, 0xffff0000, v90
	v_lshlrev_b32_e32 v16, 16, v92
	v_and_b32_e32 v17, 0xffff0000, v92
	v_lshlrev_b32_e32 v18, 16, v91
	v_and_b32_e32 v19, 0xffff0000, v91
	v_lshlrev_b32_e32 v20, 16, v93
	v_and_b32_e32 v21, 0xffff0000, v93
	v_pk_add_f32 v[90:91], v[14:15], v[16:17]
	v_pk_add_f32 v[92:93], v[18:19], v[20:21]
	v_lshlrev_b32_e32 v14, 16, v94
	v_and_b32_e32 v15, 0xffff0000, v94
	v_lshlrev_b32_e32 v16, 16, v96
	v_and_b32_e32 v17, 0xffff0000, v96
	v_lshlrev_b32_e32 v18, 16, v95
	v_and_b32_e32 v19, 0xffff0000, v95
	v_lshlrev_b32_e32 v20, 16, v97
	v_and_b32_e32 v21, 0xffff0000, v97
	v_pk_add_f32 v[94:95], v[14:15], v[16:17]
	v_pk_add_f32 v[96:97], v[18:19], v[20:21]
	v_lshlrev_b32_e32 v14, 16, v98
	v_and_b32_e32 v15, 0xffff0000, v98
	v_lshlrev_b32_e32 v16, 16, v100
	v_and_b32_e32 v17, 0xffff0000, v100
	v_lshlrev_b32_e32 v18, 16, v99
	v_and_b32_e32 v19, 0xffff0000, v99
	v_lshlrev_b32_e32 v20, 16, v101
	v_and_b32_e32 v21, 0xffff0000, v101
	v_pk_add_f32 v[98:99], v[14:15], v[16:17]
	v_pk_add_f32 v[100:101], v[18:19], v[20:21]
	v_pk_mul_f32 v[12:13], v[86:87], v[86:87]
	v_pk_fma_f32 v[12:13], v[88:89], v[88:89], v[12:13]
	v_pk_fma_f32 v[12:13], v[90:91], v[90:91], v[12:13]
	v_pk_fma_f32 v[12:13], v[92:93], v[92:93], v[12:13]
	v_pk_fma_f32 v[12:13], v[94:95], v[94:95], v[12:13]
	v_pk_fma_f32 v[12:13], v[96:97], v[96:97], v[12:13]
	v_pk_fma_f32 v[12:13], v[98:99], v[98:99], v[12:13]
	v_pk_fma_f32 v[12:13], v[100:101], v[100:101], v[12:13]
	v_add_f32_e32 v5, v12, v13
	s_nop 1
	v_add_f32_dpp v5, v5, v5 quad_perm:[1,0,3,2] row_mask:0xf bank_mask:0xf
	s_nop 1
	v_add_f32_dpp v5, v5, v5 quad_perm:[2,3,0,1] row_mask:0xf bank_mask:0xf
	s_nop 1
	v_add_f32_dpp v5, v5, v5 row_half_mirror row_mask:0xf bank_mask:0xf
	s_nop 1
	v_add_f32_dpp v5, v5, v5 row_mirror row_mask:0xf bank_mask:0xf
	s_nop 1
	v_add_f32_dpp v5, v5, v5 row_bcast:15 row_mask:0xa bank_mask:0xf
	s_nop 1
	v_add_f32_dpp v5, v5, v5 row_bcast:31 row_mask:0xc bank_mask:0xf
	s_nop 1
	v_readlane_b32 s32, v5, 63
	s_nop 1
	v_mov_b32_e32 v6, s32
	v_fmamk_f32 v6, v6, 0x3a800000, v146
	v_rsq_f32_e32 v6, v6
	s_nop 0
	v_mov_b32_e32 v8, v6
	v_pk_mul_f32 v[14:15], v[86:87], v[8:9] op_sel_hi:[1,0]
	v_pk_fma_f32 v[70:71], v[22:23], v[14:15], v[70:71]
	v_pk_mul_f32 v[14:15], v[88:89], v[8:9] op_sel_hi:[1,0]
	v_pk_fma_f32 v[72:73], v[24:25], v[14:15], v[72:73]
	v_pk_mul_f32 v[14:15], v[90:91], v[8:9] op_sel_hi:[1,0]
	v_pk_fma_f32 v[74:75], v[26:27], v[14:15], v[74:75]
	v_pk_mul_f32 v[14:15], v[92:93], v[8:9] op_sel_hi:[1,0]
	v_pk_fma_f32 v[76:77], v[28:29], v[14:15], v[76:77]
	v_pk_mul_f32 v[14:15], v[94:95], v[8:9] op_sel_hi:[1,0]
	v_pk_fma_f32 v[78:79], v[30:31], v[14:15], v[78:79]
	v_pk_mul_f32 v[14:15], v[96:97], v[8:9] op_sel_hi:[1,0]
	v_pk_fma_f32 v[80:81], v[32:33], v[14:15], v[80:81]
	v_pk_mul_f32 v[14:15], v[98:99], v[8:9] op_sel_hi:[1,0]
	v_pk_fma_f32 v[82:83], v[34:35], v[14:15], v[82:83]
	v_pk_mul_f32 v[14:15], v[100:101], v[8:9] op_sel_hi:[1,0]
	v_pk_fma_f32 v[84:85], v[36:37], v[14:15], v[84:85]
	v_pk_mul_f32 v[12:13], v[70:71], v[70:71]
	v_pk_fma_f32 v[12:13], v[72:73], v[72:73], v[12:13]
	v_pk_fma_f32 v[12:13], v[74:75], v[74:75], v[12:13]
	v_pk_fma_f32 v[12:13], v[76:77], v[76:77], v[12:13]
	v_pk_fma_f32 v[12:13], v[78:79], v[78:79], v[12:13]
	v_pk_fma_f32 v[12:13], v[80:81], v[80:81], v[12:13]
	v_pk_fma_f32 v[12:13], v[82:83], v[82:83], v[12:13]
	v_pk_fma_f32 v[12:13], v[84:85], v[84:85], v[12:13]
	v_add_f32_e32 v5, v12, v13
	s_nop 1
	v_add_f32_dpp v5, v5, v5 quad_perm:[1,0,3,2] row_mask:0xf bank_mask:0xf
	s_nop 1
	v_add_f32_dpp v5, v5, v5 quad_perm:[2,3,0,1] row_mask:0xf bank_mask:0xf
	s_nop 1
	v_add_f32_dpp v5, v5, v5 row_half_mirror row_mask:0xf bank_mask:0xf
	s_nop 1
	v_add_f32_dpp v5, v5, v5 row_mirror row_mask:0xf bank_mask:0xf
	s_nop 1
	v_add_f32_dpp v5, v5, v5 row_bcast:15 row_mask:0xa bank_mask:0xf
	s_nop 1
	v_add_f32_dpp v5, v5, v5 row_bcast:31 row_mask:0xc bank_mask:0xf
	s_nop 1
	v_readlane_b32 s32, v5, 63
	s_nop 1
	v_mov_b32_e32 v6, s32
	v_fmamk_f32 v6, v6, 0x3a800000, v146
	v_rsq_f32_e32 v6, v6
	s_nop 0
	v_mov_b32_e32 v10, v6
	v_pk_mul_f32 v[14:15], v[70:71], v[10:11] op_sel_hi:[1,0]
	v_pk_fma_f32 v[16:17], v[54:55], v[14:15], v[38:39]
	v_pk_mul_f32 v[14:15], v[72:73], v[10:11] op_sel_hi:[1,0]
	v_pk_fma_f32 v[18:19], v[56:57], v[14:15], v[40:41]
	v_cvt_pk_bf16_f32 v86, v16, v17
	v_cvt_pk_bf16_f32 v87, v18, v19
	v_pk_mul_f32 v[14:15], v[74:75], v[10:11] op_sel_hi:[1,0]
	v_pk_fma_f32 v[16:17], v[58:59], v[14:15], v[42:43]
	v_pk_mul_f32 v[14:15], v[76:77], v[10:11] op_sel_hi:[1,0]
	v_pk_fma_f32 v[18:19], v[60:61], v[14:15], v[44:45]
	v_cvt_pk_bf16_f32 v90, v16, v17
	v_cvt_pk_bf16_f32 v91, v18, v19
	v_pk_mul_f32 v[14:15], v[78:79], v[10:11] op_sel_hi:[1,0]
	v_pk_fma_f32 v[16:17], v[62:63], v[14:15], v[46:47]
	v_pk_mul_f32 v[14:15], v[80:81], v[10:11] op_sel_hi:[1,0]
	v_pk_fma_f32 v[18:19], v[64:65], v[14:15], v[48:49]
	v_cvt_pk_bf16_f32 v94, v16, v17
	v_cvt_pk_bf16_f32 v95, v18, v19
	v_pk_mul_f32 v[14:15], v[82:83], v[10:11] op_sel_hi:[1,0]
	v_pk_fma_f32 v[16:17], v[66:67], v[14:15], v[50:51]
	v_pk_mul_f32 v[14:15], v[84:85], v[10:11] op_sel_hi:[1,0]
	v_pk_fma_f32 v[18:19], v[68:69], v[14:15], v[52:53]
	v_cvt_pk_bf16_f32 v98, v16, v17
	v_cvt_pk_bf16_f32 v99, v18, v19
	global_store_dwordx2 v1, v[86:87], s[62:63] offset:0 sc1
	global_store_dwordx2 v1, v[90:91], s[62:63] offset:512 sc1
	global_store_dwordx2 v1, v[94:95], s[62:63] offset:1024 sc1
	global_store_dwordx2 v1, v[98:99], s[62:63] offset:1536 sc1
	global_store_dwordx4 v0, v[70:73], s[46:47] offset:0
	global_store_dwordx4 v0, v[74:77], s[46:47] offset:1024
	global_store_dwordx4 v0, v[78:81], s[46:47] offset:2048
	global_store_dwordx4 v0, v[82:85], s[46:47] offset:3072
	s_add_u32 s46, s46, 0x1000
	s_addc_u32 s47, s47, 0
	s_add_u32 s62, s62, 0x800
	s_addc_u32 s63, s63, 0
	s_waitcnt vmcnt(24)
	v_lshlrev_b32_e32 v14, 16, v118
	v_and_b32_e32 v15, 0xffff0000, v118
	v_lshlrev_b32_e32 v16, 16, v120
	v_and_b32_e32 v17, 0xffff0000, v120
	v_lshlrev_b32_e32 v18, 16, v119
	v_and_b32_e32 v19, 0xffff0000, v119
	v_lshlrev_b32_e32 v20, 16, v121
	v_and_b32_e32 v21, 0xffff0000, v121
	v_pk_add_f32 v[118:119], v[14:15], v[16:17]
	v_pk_add_f32 v[120:121], v[18:19], v[20:21]
	v_lshlrev_b32_e32 v14, 16, v122
	v_and_b32_e32 v15, 0xffff0000, v122
	v_lshlrev_b32_e32 v16, 16, v124
	v_and_b32_e32 v17, 0xffff0000, v124
	v_lshlrev_b32_e32 v18, 16, v123
	v_and_b32_e32 v19, 0xffff0000, v123
	v_lshlrev_b32_e32 v20, 16, v125
	v_and_b32_e32 v21, 0xffff0000, v125
	v_pk_add_f32 v[122:123], v[14:15], v[16:17]
	v_pk_add_f32 v[124:125], v[18:19], v[20:21]
	v_lshlrev_b32_e32 v14, 16, v134
	v_and_b32_e32 v15, 0xffff0000, v134
	v_lshlrev_b32_e32 v16, 16, v136
	v_and_b32_e32 v17, 0xffff0000, v136
	v_lshlrev_b32_e32 v18, 16, v135
	v_and_b32_e32 v19, 0xffff0000, v135
	v_lshlrev_b32_e32 v20, 16, v137
	v_and_b32_e32 v21, 0xffff0000, v137
	v_pk_add_f32 v[134:135], v[14:15], v[16:17]
	v_pk_add_f32 v[136:137], v[18:19], v[20:21]
	v_lshlrev_b32_e32 v14, 16, v138
	v_and_b32_e32 v15, 0xffff0000, v138
	v_lshlrev_b32_e32 v16, 16, v140
	v_and_b32_e32 v17, 0xffff0000, v140
	v_lshlrev_b32_e32 v18, 16, v139
	v_and_b32_e32 v19, 0xffff0000, v139
	v_lshlrev_b32_e32 v20, 16, v141
	v_and_b32_e32 v21, 0xffff0000, v141
	v_pk_add_f32 v[138:139], v[14:15], v[16:17]
	v_pk_add_f32 v[140:141], v[18:19], v[20:21]
	v_pk_mul_f32 v[12:13], v[118:119], v[118:119]
	v_pk_fma_f32 v[12:13], v[120:121], v[120:121], v[12:13]
	v_pk_fma_f32 v[12:13], v[122:123], v[122:123], v[12:13]
	v_pk_fma_f32 v[12:13], v[124:125], v[124:125], v[12:13]
	v_pk_fma_f32 v[12:13], v[134:135], v[134:135], v[12:13]
	v_pk_fma_f32 v[12:13], v[136:137], v[136:137], v[12:13]
	v_pk_fma_f32 v[12:13], v[138:139], v[138:139], v[12:13]
	v_pk_fma_f32 v[12:13], v[140:141], v[140:141], v[12:13]
	v_add_f32_e32 v5, v12, v13
	s_nop 1
	v_add_f32_dpp v5, v5, v5 quad_perm:[1,0,3,2] row_mask:0xf bank_mask:0xf
	s_nop 1
	v_add_f32_dpp v5, v5, v5 quad_perm:[2,3,0,1] row_mask:0xf bank_mask:0xf
	s_nop 1
	v_add_f32_dpp v5, v5, v5 row_half_mirror row_mask:0xf bank_mask:0xf
	s_nop 1
	v_add_f32_dpp v5, v5, v5 row_mirror row_mask:0xf bank_mask:0xf
	s_nop 1
	v_add_f32_dpp v5, v5, v5 row_bcast:15 row_mask:0xa bank_mask:0xf
	s_nop 1
	v_add_f32_dpp v5, v5, v5 row_bcast:31 row_mask:0xc bank_mask:0xf
	s_nop 1
	v_readlane_b32 s32, v5, 63
	s_nop 1
	v_mov_b32_e32 v6, s32
	v_fmamk_f32 v6, v6, 0x3a800000, v146
	v_rsq_f32_e32 v6, v6
	s_nop 0
	v_mov_b32_e32 v8, v6
	v_pk_mul_f32 v[14:15], v[118:119], v[8:9] op_sel_hi:[1,0]
	v_pk_fma_f32 v[102:103], v[22:23], v[14:15], v[102:103]
	v_pk_mul_f32 v[14:15], v[120:121], v[8:9] op_sel_hi:[1,0]
	v_pk_fma_f32 v[104:105], v[24:25], v[14:15], v[104:105]
	v_pk_mul_f32 v[14:15], v[122:123], v[8:9] op_sel_hi:[1,0]
	v_pk_fma_f32 v[106:107], v[26:27], v[14:15], v[106:107]
	v_pk_mul_f32 v[14:15], v[124:125], v[8:9] op_sel_hi:[1,0]
	v_pk_fma_f32 v[108:109], v[28:29], v[14:15], v[108:109]
	v_pk_mul_f32 v[14:15], v[134:135], v[8:9] op_sel_hi:[1,0]
	v_pk_fma_f32 v[110:111], v[30:31], v[14:15], v[110:111]
	v_pk_mul_f32 v[14:15], v[136:137], v[8:9] op_sel_hi:[1,0]
	v_pk_fma_f32 v[112:113], v[32:33], v[14:15], v[112:113]
	v_pk_mul_f32 v[14:15], v[138:139], v[8:9] op_sel_hi:[1,0]
	v_pk_fma_f32 v[114:115], v[34:35], v[14:15], v[114:115]
	v_pk_mul_f32 v[14:15], v[140:141], v[8:9] op_sel_hi:[1,0]
	v_pk_fma_f32 v[116:117], v[36:37], v[14:15], v[116:117]
	v_pk_mul_f32 v[12:13], v[102:103], v[102:103]
	v_pk_fma_f32 v[12:13], v[104:105], v[104:105], v[12:13]
	v_pk_fma_f32 v[12:13], v[106:107], v[106:107], v[12:13]
	v_pk_fma_f32 v[12:13], v[108:109], v[108:109], v[12:13]
	v_pk_fma_f32 v[12:13], v[110:111], v[110:111], v[12:13]
	v_pk_fma_f32 v[12:13], v[112:113], v[112:113], v[12:13]
	v_pk_fma_f32 v[12:13], v[114:115], v[114:115], v[12:13]
	v_pk_fma_f32 v[12:13], v[116:117], v[116:117], v[12:13]
	v_add_f32_e32 v5, v12, v13
	s_nop 1
	v_add_f32_dpp v5, v5, v5 quad_perm:[1,0,3,2] row_mask:0xf bank_mask:0xf
	s_nop 1
	v_add_f32_dpp v5, v5, v5 quad_perm:[2,3,0,1] row_mask:0xf bank_mask:0xf
	s_nop 1
	v_add_f32_dpp v5, v5, v5 row_half_mirror row_mask:0xf bank_mask:0xf
	s_nop 1
	v_add_f32_dpp v5, v5, v5 row_mirror row_mask:0xf bank_mask:0xf
	s_nop 1
	v_add_f32_dpp v5, v5, v5 row_bcast:15 row_mask:0xa bank_mask:0xf
	s_nop 1
	v_add_f32_dpp v5, v5, v5 row_bcast:31 row_mask:0xc bank_mask:0xf
	s_nop 1
	v_readlane_b32 s32, v5, 63
	s_nop 1
	v_mov_b32_e32 v6, s32
	v_fmamk_f32 v6, v6, 0x3a800000, v146
	v_rsq_f32_e32 v6, v6
	s_nop 0
	v_mov_b32_e32 v10, v6
	v_pk_mul_f32 v[14:15], v[102:103], v[10:11] op_sel_hi:[1,0]
	v_pk_fma_f32 v[16:17], v[54:55], v[14:15], v[38:39]
	v_pk_mul_f32 v[14:15], v[104:105], v[10:11] op_sel_hi:[1,0]
	v_pk_fma_f32 v[18:19], v[56:57], v[14:15], v[40:41]
	v_cvt_pk_bf16_f32 v118, v16, v17
	v_cvt_pk_bf16_f32 v119, v18, v19
	v_pk_mul_f32 v[14:15], v[106:107], v[10:11] op_sel_hi:[1,0]
	v_pk_fma_f32 v[16:17], v[58:59], v[14:15], v[42:43]
	v_pk_mul_f32 v[14:15], v[108:109], v[10:11] op_sel_hi:[1,0]
	v_pk_fma_f32 v[18:19], v[60:61], v[14:15], v[44:45]
	v_cvt_pk_bf16_f32 v122, v16, v17
	v_cvt_pk_bf16_f32 v123, v18, v19
	v_pk_mul_f32 v[14:15], v[110:111], v[10:11] op_sel_hi:[1,0]
	v_pk_fma_f32 v[16:17], v[62:63], v[14:15], v[46:47]
	v_pk_mul_f32 v[14:15], v[112:113], v[10:11] op_sel_hi:[1,0]
	v_pk_fma_f32 v[18:19], v[64:65], v[14:15], v[48:49]
	v_cvt_pk_bf16_f32 v134, v16, v17
	v_cvt_pk_bf16_f32 v135, v18, v19
	v_pk_mul_f32 v[14:15], v[114:115], v[10:11] op_sel_hi:[1,0]
	v_pk_fma_f32 v[16:17], v[66:67], v[14:15], v[50:51]
	v_pk_mul_f32 v[14:15], v[116:117], v[10:11] op_sel_hi:[1,0]
	v_pk_fma_f32 v[18:19], v[68:69], v[14:15], v[52:53]
	v_cvt_pk_bf16_f32 v138, v16, v17
	v_cvt_pk_bf16_f32 v139, v18, v19
	global_store_dwordx2 v1, v[118:119], s[62:63] offset:0 sc1
	global_store_dwordx2 v1, v[122:123], s[62:63] offset:512 sc1
	global_store_dwordx2 v1, v[134:135], s[62:63] offset:1024 sc1
	global_store_dwordx2 v1, v[138:139], s[62:63] offset:1536 sc1
	global_store_dwordx4 v0, v[102:105], s[46:47] offset:0
	global_store_dwordx4 v0, v[106:109], s[46:47] offset:1024
	global_store_dwordx4 v0, v[110:113], s[46:47] offset:2048
	global_store_dwordx4 v0, v[114:117], s[46:47] offset:3072
	s_add_u32 s46, s46, 0x1000
	s_addc_u32 s47, s47, 0
	s_add_u32 s62, s62, 0x800
	s_addc_u32 s63, s63, 0
	s_waitcnt vmcnt(24)
	v_lshlrev_b32_e32 v14, 16, v172
	v_and_b32_e32 v15, 0xffff0000, v172
	v_lshlrev_b32_e32 v16, 16, v174
	v_and_b32_e32 v17, 0xffff0000, v174
	v_lshlrev_b32_e32 v18, 16, v173
	v_and_b32_e32 v19, 0xffff0000, v173
	v_lshlrev_b32_e32 v20, 16, v175
	v_and_b32_e32 v21, 0xffff0000, v175
	v_pk_add_f32 v[172:173], v[14:15], v[16:17]
	v_pk_add_f32 v[174:175], v[18:19], v[20:21]
	v_lshlrev_b32_e32 v14, 16, v176
	v_and_b32_e32 v15, 0xffff0000, v176
	v_lshlrev_b32_e32 v16, 16, v178
	v_and_b32_e32 v17, 0xffff0000, v178
	v_lshlrev_b32_e32 v18, 16, v177
	v_and_b32_e32 v19, 0xffff0000, v177
	v_lshlrev_b32_e32 v20, 16, v179
	v_and_b32_e32 v21, 0xffff0000, v179
	v_pk_add_f32 v[176:177], v[14:15], v[16:17]
	v_pk_add_f32 v[178:179], v[18:19], v[20:21]
	v_lshlrev_b32_e32 v14, 16, v204
	v_and_b32_e32 v15, 0xffff0000, v204
	v_lshlrev_b32_e32 v16, 16, v206
	v_and_b32_e32 v17, 0xffff0000, v206
	v_lshlrev_b32_e32 v18, 16, v205
	v_and_b32_e32 v19, 0xffff0000, v205
	v_lshlrev_b32_e32 v20, 16, v207
	v_and_b32_e32 v21, 0xffff0000, v207
	v_pk_add_f32 v[204:205], v[14:15], v[16:17]
	v_pk_add_f32 v[206:207], v[18:19], v[20:21]
	v_lshlrev_b32_e32 v14, 16, v214
	v_and_b32_e32 v15, 0xffff0000, v214
	v_lshlrev_b32_e32 v16, 16, v216
	v_and_b32_e32 v17, 0xffff0000, v216
	v_lshlrev_b32_e32 v18, 16, v215
	v_and_b32_e32 v19, 0xffff0000, v215
	v_lshlrev_b32_e32 v20, 16, v217
	v_and_b32_e32 v21, 0xffff0000, v217
	v_pk_add_f32 v[214:215], v[14:15], v[16:17]
	v_pk_add_f32 v[216:217], v[18:19], v[20:21]
	v_pk_mul_f32 v[12:13], v[172:173], v[172:173]
	v_pk_fma_f32 v[12:13], v[174:175], v[174:175], v[12:13]
	v_pk_fma_f32 v[12:13], v[176:177], v[176:177], v[12:13]
	v_pk_fma_f32 v[12:13], v[178:179], v[178:179], v[12:13]
	v_pk_fma_f32 v[12:13], v[204:205], v[204:205], v[12:13]
	v_pk_fma_f32 v[12:13], v[206:207], v[206:207], v[12:13]
	v_pk_fma_f32 v[12:13], v[214:215], v[214:215], v[12:13]
	v_pk_fma_f32 v[12:13], v[216:217], v[216:217], v[12:13]
	v_add_f32_e32 v5, v12, v13
	s_nop 1
	v_add_f32_dpp v5, v5, v5 quad_perm:[1,0,3,2] row_mask:0xf bank_mask:0xf
	s_nop 1
	v_add_f32_dpp v5, v5, v5 quad_perm:[2,3,0,1] row_mask:0xf bank_mask:0xf
	s_nop 1
	v_add_f32_dpp v5, v5, v5 row_half_mirror row_mask:0xf bank_mask:0xf
	s_nop 1
	v_add_f32_dpp v5, v5, v5 row_mirror row_mask:0xf bank_mask:0xf
	s_nop 1
	v_add_f32_dpp v5, v5, v5 row_bcast:15 row_mask:0xa bank_mask:0xf
	s_nop 1
	v_add_f32_dpp v5, v5, v5 row_bcast:31 row_mask:0xc bank_mask:0xf
	s_nop 1
	v_readlane_b32 s32, v5, 63
	s_nop 1
	v_mov_b32_e32 v6, s32
	v_fmamk_f32 v6, v6, 0x3a800000, v146
	v_rsq_f32_e32 v6, v6
	s_nop 0
	v_mov_b32_e32 v8, v6
	v_pk_mul_f32 v[14:15], v[172:173], v[8:9] op_sel_hi:[1,0]
	v_pk_fma_f32 v[154:155], v[22:23], v[14:15], v[154:155]
	v_pk_mul_f32 v[14:15], v[174:175], v[8:9] op_sel_hi:[1,0]
	v_pk_fma_f32 v[156:157], v[24:25], v[14:15], v[156:157]
	v_pk_mul_f32 v[14:15], v[176:177], v[8:9] op_sel_hi:[1,0]
	v_pk_fma_f32 v[158:159], v[26:27], v[14:15], v[158:159]
	v_pk_mul_f32 v[14:15], v[178:179], v[8:9] op_sel_hi:[1,0]
	v_pk_fma_f32 v[160:161], v[28:29], v[14:15], v[160:161]
	v_pk_mul_f32 v[14:15], v[204:205], v[8:9] op_sel_hi:[1,0]
	v_pk_fma_f32 v[162:163], v[30:31], v[14:15], v[162:163]
	v_pk_mul_f32 v[14:15], v[206:207], v[8:9] op_sel_hi:[1,0]
	v_pk_fma_f32 v[164:165], v[32:33], v[14:15], v[164:165]
	v_pk_mul_f32 v[14:15], v[214:215], v[8:9] op_sel_hi:[1,0]
	v_pk_fma_f32 v[168:169], v[34:35], v[14:15], v[168:169]
	v_pk_mul_f32 v[14:15], v[216:217], v[8:9] op_sel_hi:[1,0]
	v_pk_fma_f32 v[170:171], v[36:37], v[14:15], v[170:171]
	v_pk_mul_f32 v[12:13], v[154:155], v[154:155]
	v_pk_fma_f32 v[12:13], v[156:157], v[156:157], v[12:13]
	v_pk_fma_f32 v[12:13], v[158:159], v[158:159], v[12:13]
	v_pk_fma_f32 v[12:13], v[160:161], v[160:161], v[12:13]
	v_pk_fma_f32 v[12:13], v[162:163], v[162:163], v[12:13]
	v_pk_fma_f32 v[12:13], v[164:165], v[164:165], v[12:13]
	v_pk_fma_f32 v[12:13], v[168:169], v[168:169], v[12:13]
	v_pk_fma_f32 v[12:13], v[170:171], v[170:171], v[12:13]
	v_add_f32_e32 v5, v12, v13
	s_nop 1
	v_add_f32_dpp v5, v5, v5 quad_perm:[1,0,3,2] row_mask:0xf bank_mask:0xf
	s_nop 1
	v_add_f32_dpp v5, v5, v5 quad_perm:[2,3,0,1] row_mask:0xf bank_mask:0xf
	s_nop 1
	v_add_f32_dpp v5, v5, v5 row_half_mirror row_mask:0xf bank_mask:0xf
	s_nop 1
	v_add_f32_dpp v5, v5, v5 row_mirror row_mask:0xf bank_mask:0xf
	s_nop 1
	v_add_f32_dpp v5, v5, v5 row_bcast:15 row_mask:0xa bank_mask:0xf
	s_nop 1
	v_add_f32_dpp v5, v5, v5 row_bcast:31 row_mask:0xc bank_mask:0xf
	s_nop 1
	v_readlane_b32 s32, v5, 63
	s_nop 1
	v_mov_b32_e32 v6, s32
	v_fmamk_f32 v6, v6, 0x3a800000, v146
	v_rsq_f32_e32 v6, v6
	s_nop 0
	v_mov_b32_e32 v10, v6
	v_pk_mul_f32 v[14:15], v[154:155], v[10:11] op_sel_hi:[1,0]
	v_pk_fma_f32 v[16:17], v[54:55], v[14:15], v[38:39]
	v_pk_mul_f32 v[14:15], v[156:157], v[10:11] op_sel_hi:[1,0]
	v_pk_fma_f32 v[18:19], v[56:57], v[14:15], v[40:41]
	v_cvt_pk_bf16_f32 v172, v16, v17
	v_cvt_pk_bf16_f32 v173, v18, v19
	v_pk_mul_f32 v[14:15], v[158:159], v[10:11] op_sel_hi:[1,0]
	v_pk_fma_f32 v[16:17], v[58:59], v[14:15], v[42:43]
	v_pk_mul_f32 v[14:15], v[160:161], v[10:11] op_sel_hi:[1,0]
	v_pk_fma_f32 v[18:19], v[60:61], v[14:15], v[44:45]
	v_cvt_pk_bf16_f32 v176, v16, v17
	v_cvt_pk_bf16_f32 v177, v18, v19
	v_pk_mul_f32 v[14:15], v[162:163], v[10:11] op_sel_hi:[1,0]
	v_pk_fma_f32 v[16:17], v[62:63], v[14:15], v[46:47]
	v_pk_mul_f32 v[14:15], v[164:165], v[10:11] op_sel_hi:[1,0]
	v_pk_fma_f32 v[18:19], v[64:65], v[14:15], v[48:49]
	v_cvt_pk_bf16_f32 v204, v16, v17
	v_cvt_pk_bf16_f32 v205, v18, v19
	v_pk_mul_f32 v[14:15], v[168:169], v[10:11] op_sel_hi:[1,0]
	v_pk_fma_f32 v[16:17], v[66:67], v[14:15], v[50:51]
	v_pk_mul_f32 v[14:15], v[170:171], v[10:11] op_sel_hi:[1,0]
	v_pk_fma_f32 v[18:19], v[68:69], v[14:15], v[52:53]
	v_cvt_pk_bf16_f32 v214, v16, v17
	v_cvt_pk_bf16_f32 v215, v18, v19
	global_store_dwordx2 v1, v[172:173], s[62:63] offset:0 sc1
	global_store_dwordx2 v1, v[176:177], s[62:63] offset:512 sc1
	global_store_dwordx2 v1, v[204:205], s[62:63] offset:1024 sc1
	global_store_dwordx2 v1, v[214:215], s[62:63] offset:1536 sc1
	global_store_dwordx4 v0, v[154:157], s[46:47] offset:0
	global_store_dwordx4 v0, v[158:161], s[46:47] offset:1024
	global_store_dwordx4 v0, v[162:165], s[46:47] offset:2048
	global_store_dwordx4 v0, v[168:171], s[46:47] offset:3072
	s_add_u32 s46, s46, 0x1000
	s_addc_u32 s47, s47, 0
	s_add_u32 s62, s62, 0x800
	s_addc_u32 s63, s63, 0
	s_waitcnt vmcnt(24)
	v_lshlrev_b32_e32 v14, 16, v234
	v_and_b32_e32 v15, 0xffff0000, v234
	v_lshlrev_b32_e32 v16, 16, v236
	v_and_b32_e32 v17, 0xffff0000, v236
	v_lshlrev_b32_e32 v18, 16, v235
	v_and_b32_e32 v19, 0xffff0000, v235
	v_lshlrev_b32_e32 v20, 16, v237
	v_and_b32_e32 v21, 0xffff0000, v237
	v_pk_add_f32 v[234:235], v[14:15], v[16:17]
	v_pk_add_f32 v[236:237], v[18:19], v[20:21]
	v_lshlrev_b32_e32 v14, 16, v238
	v_and_b32_e32 v15, 0xffff0000, v238
	v_lshlrev_b32_e32 v16, 16, v240
	v_and_b32_e32 v17, 0xffff0000, v240
	v_lshlrev_b32_e32 v18, 16, v239
	v_and_b32_e32 v19, 0xffff0000, v239
	v_lshlrev_b32_e32 v20, 16, v241
	v_and_b32_e32 v21, 0xffff0000, v241
	v_pk_add_f32 v[238:239], v[14:15], v[16:17]
	v_pk_add_f32 v[240:241], v[18:19], v[20:21]
	v_lshlrev_b32_e32 v14, 16, v242
	v_and_b32_e32 v15, 0xffff0000, v242
	v_lshlrev_b32_e32 v16, 16, v244
	v_and_b32_e32 v17, 0xffff0000, v244
	v_lshlrev_b32_e32 v18, 16, v243
	v_and_b32_e32 v19, 0xffff0000, v243
	v_lshlrev_b32_e32 v20, 16, v245
	v_and_b32_e32 v21, 0xffff0000, v245
	v_pk_add_f32 v[242:243], v[14:15], v[16:17]
	v_pk_add_f32 v[244:245], v[18:19], v[20:21]
	v_lshlrev_b32_e32 v14, 16, v246
	v_and_b32_e32 v15, 0xffff0000, v246
	v_lshlrev_b32_e32 v16, 16, v248
	v_and_b32_e32 v17, 0xffff0000, v248
	v_lshlrev_b32_e32 v18, 16, v247
	v_and_b32_e32 v19, 0xffff0000, v247
	v_lshlrev_b32_e32 v20, 16, v249
	v_and_b32_e32 v21, 0xffff0000, v249
	v_pk_add_f32 v[246:247], v[14:15], v[16:17]
	v_pk_add_f32 v[248:249], v[18:19], v[20:21]
	v_pk_mul_f32 v[12:13], v[234:235], v[234:235]
	v_pk_fma_f32 v[12:13], v[236:237], v[236:237], v[12:13]
	v_pk_fma_f32 v[12:13], v[238:239], v[238:239], v[12:13]
	v_pk_fma_f32 v[12:13], v[240:241], v[240:241], v[12:13]
	v_pk_fma_f32 v[12:13], v[242:243], v[242:243], v[12:13]
	v_pk_fma_f32 v[12:13], v[244:245], v[244:245], v[12:13]
	v_pk_fma_f32 v[12:13], v[246:247], v[246:247], v[12:13]
	v_pk_fma_f32 v[12:13], v[248:249], v[248:249], v[12:13]
	v_add_f32_e32 v5, v12, v13
	s_nop 1
	v_add_f32_dpp v5, v5, v5 quad_perm:[1,0,3,2] row_mask:0xf bank_mask:0xf
	s_nop 1
	v_add_f32_dpp v5, v5, v5 quad_perm:[2,3,0,1] row_mask:0xf bank_mask:0xf
	s_nop 1
	v_add_f32_dpp v5, v5, v5 row_half_mirror row_mask:0xf bank_mask:0xf
	s_nop 1
	v_add_f32_dpp v5, v5, v5 row_mirror row_mask:0xf bank_mask:0xf
	s_nop 1
	v_add_f32_dpp v5, v5, v5 row_bcast:15 row_mask:0xa bank_mask:0xf
	s_nop 1
	v_add_f32_dpp v5, v5, v5 row_bcast:31 row_mask:0xc bank_mask:0xf
	s_nop 1
	v_readlane_b32 s32, v5, 63
	s_nop 1
	v_mov_b32_e32 v6, s32
	v_fmamk_f32 v6, v6, 0x3a800000, v146
	v_rsq_f32_e32 v6, v6
	s_nop 0
	v_mov_b32_e32 v8, v6
	v_pk_mul_f32 v[14:15], v[234:235], v[8:9] op_sel_hi:[1,0]
	v_pk_fma_f32 v[218:219], v[22:23], v[14:15], v[218:219]
	v_pk_mul_f32 v[14:15], v[236:237], v[8:9] op_sel_hi:[1,0]
	v_pk_fma_f32 v[220:221], v[24:25], v[14:15], v[220:221]
	v_pk_mul_f32 v[14:15], v[238:239], v[8:9] op_sel_hi:[1,0]
	v_pk_fma_f32 v[222:223], v[26:27], v[14:15], v[222:223]
	v_pk_mul_f32 v[14:15], v[240:241], v[8:9] op_sel_hi:[1,0]
	v_pk_fma_f32 v[224:225], v[28:29], v[14:15], v[224:225]
	v_pk_mul_f32 v[14:15], v[242:243], v[8:9] op_sel_hi:[1,0]
	v_pk_fma_f32 v[226:227], v[30:31], v[14:15], v[226:227]
	v_pk_mul_f32 v[14:15], v[244:245], v[8:9] op_sel_hi:[1,0]
	v_pk_fma_f32 v[228:229], v[32:33], v[14:15], v[228:229]
	v_pk_mul_f32 v[14:15], v[246:247], v[8:9] op_sel_hi:[1,0]
	v_pk_fma_f32 v[230:231], v[34:35], v[14:15], v[230:231]
	v_pk_mul_f32 v[14:15], v[248:249], v[8:9] op_sel_hi:[1,0]
	v_pk_fma_f32 v[232:233], v[36:37], v[14:15], v[232:233]
	v_pk_mul_f32 v[12:13], v[218:219], v[218:219]
	v_pk_fma_f32 v[12:13], v[220:221], v[220:221], v[12:13]
	v_pk_fma_f32 v[12:13], v[222:223], v[222:223], v[12:13]
	v_pk_fma_f32 v[12:13], v[224:225], v[224:225], v[12:13]
	v_pk_fma_f32 v[12:13], v[226:227], v[226:227], v[12:13]
	v_pk_fma_f32 v[12:13], v[228:229], v[228:229], v[12:13]
	v_pk_fma_f32 v[12:13], v[230:231], v[230:231], v[12:13]
	v_pk_fma_f32 v[12:13], v[232:233], v[232:233], v[12:13]
	v_add_f32_e32 v5, v12, v13
	s_nop 1
	v_add_f32_dpp v5, v5, v5 quad_perm:[1,0,3,2] row_mask:0xf bank_mask:0xf
	s_nop 1
	v_add_f32_dpp v5, v5, v5 quad_perm:[2,3,0,1] row_mask:0xf bank_mask:0xf
	s_nop 1
	v_add_f32_dpp v5, v5, v5 row_half_mirror row_mask:0xf bank_mask:0xf
	s_nop 1
	v_add_f32_dpp v5, v5, v5 row_mirror row_mask:0xf bank_mask:0xf
	s_nop 1
	v_add_f32_dpp v5, v5, v5 row_bcast:15 row_mask:0xa bank_mask:0xf
	s_nop 1
	v_add_f32_dpp v5, v5, v5 row_bcast:31 row_mask:0xc bank_mask:0xf
	s_nop 1
	v_readlane_b32 s32, v5, 63
	s_nop 1
	v_mov_b32_e32 v6, s32
	v_fmamk_f32 v6, v6, 0x3a800000, v146
	v_rsq_f32_e32 v6, v6
	s_nop 0
	v_mov_b32_e32 v10, v6
	v_pk_mul_f32 v[14:15], v[218:219], v[10:11] op_sel_hi:[1,0]
	v_pk_fma_f32 v[16:17], v[54:55], v[14:15], v[38:39]
	v_pk_mul_f32 v[14:15], v[220:221], v[10:11] op_sel_hi:[1,0]
	v_pk_fma_f32 v[18:19], v[56:57], v[14:15], v[40:41]
	v_cvt_pk_bf16_f32 v234, v16, v17
	v_cvt_pk_bf16_f32 v235, v18, v19
	v_pk_mul_f32 v[14:15], v[222:223], v[10:11] op_sel_hi:[1,0]
	v_pk_fma_f32 v[16:17], v[58:59], v[14:15], v[42:43]
	v_pk_mul_f32 v[14:15], v[224:225], v[10:11] op_sel_hi:[1,0]
	v_pk_fma_f32 v[18:19], v[60:61], v[14:15], v[44:45]
	v_cvt_pk_bf16_f32 v238, v16, v17
	v_cvt_pk_bf16_f32 v239, v18, v19
	v_pk_mul_f32 v[14:15], v[226:227], v[10:11] op_sel_hi:[1,0]
	v_pk_fma_f32 v[16:17], v[62:63], v[14:15], v[46:47]
	v_pk_mul_f32 v[14:15], v[228:229], v[10:11] op_sel_hi:[1,0]
	v_pk_fma_f32 v[18:19], v[64:65], v[14:15], v[48:49]
	v_cvt_pk_bf16_f32 v242, v16, v17
	v_cvt_pk_bf16_f32 v243, v18, v19
	v_pk_mul_f32 v[14:15], v[230:231], v[10:11] op_sel_hi:[1,0]
	v_pk_fma_f32 v[16:17], v[66:67], v[14:15], v[50:51]
	v_pk_mul_f32 v[14:15], v[232:233], v[10:11] op_sel_hi:[1,0]
	v_pk_fma_f32 v[18:19], v[68:69], v[14:15], v[52:53]
	v_cvt_pk_bf16_f32 v246, v16, v17
	v_cvt_pk_bf16_f32 v247, v18, v19
	global_store_dwordx2 v1, v[234:235], s[62:63] offset:0 sc1
	global_store_dwordx2 v1, v[238:239], s[62:63] offset:512 sc1
	global_store_dwordx2 v1, v[242:243], s[62:63] offset:1024 sc1
	global_store_dwordx2 v1, v[246:247], s[62:63] offset:1536 sc1
	global_store_dwordx4 v0, v[218:221], s[46:47] offset:0
	global_store_dwordx4 v0, v[222:225], s[46:47] offset:1024
	global_store_dwordx4 v0, v[226:229], s[46:47] offset:2048
	global_store_dwordx4 v0, v[230:233], s[46:47] offset:3072
	s_add_u32 s46, s46, 0x1000
	s_addc_u32 s47, s47, 0
	s_add_u32 s62, s62, 0x800
	s_addc_u32 s63, s63, 0
.LBB0_1225:
	s_or_b64 exec, exec, s[10:11]
	s_waitcnt vmcnt(0)
	v_mov_b32_e32 v0, v147
	s_barrier
	s_nop 0
	v_readfirstlane_b32 vcc_lo, v0
	s_nop 1
	s_cmp_eq_u32 vcc_lo, 64
	s_cbranch_scc0 .Lxb_noinv_8
	buffer_inv sc1
.Lxb_noinv_8:
	v_cmp_eq_u32_e32 vcc, 0, v0
	s_and_saveexec_b64 s[4:5], vcc
	s_cbranch_execz .LBB0_334
	s_load_dwordx2 s[12:13], s[8:9], 0x98
	v_readlane_b32 s14, v255, 0
	v_readlane_b32 s15, v255, 47
	s_nop 0
	s_lshr_b32 s24, s14, 3
	s_and_b32 s24, s24, 7
	s_and_b32 s27, s14, 6
	s_lshl_b32 s27, s27, 2
	s_or_b32 s27, s27, s24
	s_and_b32 s30, s14, 3
	s_lshl_b32 s30, s30, 3
	s_or_b32 s30, s30, s24
	s_lshl_b32 s27, s27, 7
	s_add_u32 s27, s27, 0xb000
	s_add_u32 s15, s15, 8
	v_writelane_b32 v255, s15, 47
	v_mov_b32_e32 v0, s27
	s_waitcnt lgkmcnt(0)
	global_atomic_add v0, v189, s[12:13]
	v_writelane_b32 v255, s27, 50
	v_writelane_b32 v255, s15, 51
	v_writelane_b32 v255, s27, 52
	v_writelane_b32 v255, s15, 53
	v_writelane_b32 v255, s12, 54
	v_writelane_b32 v255, s13, 55
	s_branch .LBB0_334

.Lnw_skip_n3:
	s_or_b64 exec, exec, s[40:41]
	s_waitcnt vmcnt(24)
	s_barrier
	global_load_dwordx2 v[54:55], v1, s[58:59] offset:0
	global_load_dwordx2 v[58:59], v1, s[58:59] offset:512
	global_load_dwordx2 v[62:63], v1, s[58:59] offset:1024
	global_load_dwordx2 v[66:67], v1, s[58:59] offset:1536
	global_load_dwordx2 v[56:57], v1, s[60:61] offset:0
	global_load_dwordx2 v[60:61], v1, s[60:61] offset:512
	global_load_dwordx2 v[64:65], v1, s[60:61] offset:1024
	global_load_dwordx2 v[68:69], v1, s[60:61] offset:1536
	s_add_u32 s58, s58, 0x800
	s_addc_u32 s59, s59, 0
	s_add_u32 s60, s60, 0x800
	s_addc_u32 s61, s61, 0
	global_load_dwordx2 v[86:87], v1, s[58:59] offset:0
	global_load_dwordx2 v[90:91], v1, s[58:59] offset:512
	global_load_dwordx2 v[94:95], v1, s[58:59] offset:1024
	global_load_dwordx2 v[98:99], v1, s[58:59] offset:1536
	global_load_dwordx2 v[88:89], v1, s[60:61] offset:0
	global_load_dwordx2 v[92:93], v1, s[60:61] offset:512
	global_load_dwordx2 v[96:97], v1, s[60:61] offset:1024
	global_load_dwordx2 v[100:101], v1, s[60:61] offset:1536
	s_add_u32 s58, s58, 0x800
	s_addc_u32 s59, s59, 0
	s_add_u32 s60, s60, 0x800
	s_addc_u32 s61, s61, 0
	global_load_dwordx2 v[118:119], v1, s[58:59] offset:0
	global_load_dwordx2 v[122:123], v1, s[58:59] offset:512
	global_load_dwordx2 v[134:135], v1, s[58:59] offset:1024
	global_load_dwordx2 v[138:139], v1, s[58:59] offset:1536
	global_load_dwordx2 v[120:121], v1, s[60:61] offset:0
	global_load_dwordx2 v[124:125], v1, s[60:61] offset:512
	global_load_dwordx2 v[136:137], v1, s[60:61] offset:1024
	global_load_dwordx2 v[140:141], v1, s[60:61] offset:1536
	s_add_u32 s58, s58, 0x800
	s_addc_u32 s59, s59, 0
	s_add_u32 s60, s60, 0x800
	s_addc_u32 s61, s61, 0
	global_load_dwordx2 v[172:173], v1, s[58:59] offset:0
	global_load_dwordx2 v[176:177], v1, s[58:59] offset:512
	global_load_dwordx2 v[204:205], v1, s[58:59] offset:1024
	global_load_dwordx2 v[214:215], v1, s[58:59] offset:1536
	global_load_dwordx2 v[174:175], v1, s[60:61] offset:0
	global_load_dwordx2 v[178:179], v1, s[60:61] offset:512
	global_load_dwordx2 v[206:207], v1, s[60:61] offset:1024
	global_load_dwordx2 v[216:217], v1, s[60:61] offset:1536
	s_add_u32 s58, s58, 0x800
	s_addc_u32 s59, s59, 0
	s_add_u32 s60, s60, 0x800
	s_addc_u32 s61, s61, 0
	s_waitcnt vmcnt(24)
	v_lshlrev_b32_e32 v14, 16, v54
	v_and_b32_e32 v15, 0xffff0000, v54
	v_lshlrev_b32_e32 v16, 16, v56
	v_and_b32_e32 v17, 0xffff0000, v56
	v_lshlrev_b32_e32 v18, 16, v55
	v_and_b32_e32 v19, 0xffff0000, v55
	v_lshlrev_b32_e32 v20, 16, v57
	v_and_b32_e32 v21, 0xffff0000, v57
	v_pk_add_f32 v[54:55], v[14:15], v[16:17]
	v_pk_add_f32 v[56:57], v[18:19], v[20:21]
	v_lshlrev_b32_e32 v14, 16, v58
	v_and_b32_e32 v15, 0xffff0000, v58
	v_lshlrev_b32_e32 v16, 16, v60
	v_and_b32_e32 v17, 0xffff0000, v60
	v_lshlrev_b32_e32 v18, 16, v59
	v_and_b32_e32 v19, 0xffff0000, v59
	v_lshlrev_b32_e32 v20, 16, v61
	v_and_b32_e32 v21, 0xffff0000, v61
	v_pk_add_f32 v[58:59], v[14:15], v[16:17]
	v_pk_add_f32 v[60:61], v[18:19], v[20:21]
	v_lshlrev_b32_e32 v14, 16, v62
	v_and_b32_e32 v15, 0xffff0000, v62
	v_lshlrev_b32_e32 v16, 16, v64
	v_and_b32_e32 v17, 0xffff0000, v64
	v_lshlrev_b32_e32 v18, 16, v63
	v_and_b32_e32 v19, 0xffff0000, v63
	v_lshlrev_b32_e32 v20, 16, v65
	v_and_b32_e32 v21, 0xffff0000, v65
	v_pk_add_f32 v[62:63], v[14:15], v[16:17]
	v_pk_add_f32 v[64:65], v[18:19], v[20:21]
	v_lshlrev_b32_e32 v14, 16, v66
	v_and_b32_e32 v15, 0xffff0000, v66
	v_lshlrev_b32_e32 v16, 16, v68
	v_and_b32_e32 v17, 0xffff0000, v68
	v_lshlrev_b32_e32 v18, 16, v67
	v_and_b32_e32 v19, 0xffff0000, v67
	v_lshlrev_b32_e32 v20, 16, v69
	v_and_b32_e32 v21, 0xffff0000, v69
	v_pk_add_f32 v[66:67], v[14:15], v[16:17]
	v_pk_add_f32 v[68:69], v[18:19], v[20:21]
	v_pk_mul_f32 v[12:13], v[54:55], v[54:55]
	v_pk_fma_f32 v[12:13], v[56:57], v[56:57], v[12:13]
	v_pk_fma_f32 v[12:13], v[58:59], v[58:59], v[12:13]
	v_pk_fma_f32 v[12:13], v[60:61], v[60:61], v[12:13]
	v_pk_fma_f32 v[12:13], v[62:63], v[62:63], v[12:13]
	v_pk_fma_f32 v[12:13], v[64:65], v[64:65], v[12:13]
	v_pk_fma_f32 v[12:13], v[66:67], v[66:67], v[12:13]
	v_pk_fma_f32 v[12:13], v[68:69], v[68:69], v[12:13]
	v_add_f32_e32 v5, v12, v13
	s_nop 1
	v_add_f32_dpp v5, v5, v5 quad_perm:[1,0,3,2] row_mask:0xf bank_mask:0xf
	s_nop 1
	v_add_f32_dpp v5, v5, v5 quad_perm:[2,3,0,1] row_mask:0xf bank_mask:0xf
	s_nop 1
	v_add_f32_dpp v5, v5, v5 row_half_mirror row_mask:0xf bank_mask:0xf
	s_nop 1
	v_add_f32_dpp v5, v5, v5 row_mirror row_mask:0xf bank_mask:0xf
	s_nop 1
	v_add_f32_dpp v5, v5, v5 row_bcast:15 row_mask:0xa bank_mask:0xf
	s_nop 1
	v_add_f32_dpp v5, v5, v5 row_bcast:31 row_mask:0xc bank_mask:0xf
	s_nop 1
	v_readlane_b32 s32, v5, 63
	s_nop 1
	v_mov_b32_e32 v6, s32
	v_fmamk_f32 v6, v6, 0x3a800000, v146
	v_rsq_f32_e32 v6, v6
	s_nop 0
	v_mul_f32_e32 v8, 0.5, v6
	v_pk_mul_f32 v[14:15], v[54:55], v[8:9] op_sel_hi:[1,0]
	v_pk_fma_f32 v[38:39], v[22:23], v[14:15], v[38:39]
	v_pk_mul_f32 v[14:15], v[56:57], v[8:9] op_sel_hi:[1,0]
	v_pk_fma_f32 v[40:41], v[24:25], v[14:15], v[40:41]
	v_pk_mul_f32 v[14:15], v[58:59], v[8:9] op_sel_hi:[1,0]
	v_pk_fma_f32 v[42:43], v[26:27], v[14:15], v[42:43]
	v_pk_mul_f32 v[14:15], v[60:61], v[8:9] op_sel_hi:[1,0]
	v_pk_fma_f32 v[44:45], v[28:29], v[14:15], v[44:45]
	v_pk_mul_f32 v[14:15], v[62:63], v[8:9] op_sel_hi:[1,0]
	v_pk_fma_f32 v[46:47], v[30:31], v[14:15], v[46:47]
	v_pk_mul_f32 v[14:15], v[64:65], v[8:9] op_sel_hi:[1,0]
	v_pk_fma_f32 v[48:49], v[32:33], v[14:15], v[48:49]
	v_pk_mul_f32 v[14:15], v[66:67], v[8:9] op_sel_hi:[1,0]
	v_pk_fma_f32 v[50:51], v[34:35], v[14:15], v[50:51]
	v_pk_mul_f32 v[14:15], v[68:69], v[8:9] op_sel_hi:[1,0]
	v_pk_fma_f32 v[52:53], v[36:37], v[14:15], v[52:53]
	global_store_dwordx4 v0, v[38:41], s[46:47] offset:0
	global_store_dwordx4 v0, v[42:45], s[46:47] offset:1024
	global_store_dwordx4 v0, v[46:49], s[46:47] offset:2048
	global_store_dwordx4 v0, v[50:53], s[46:47] offset:3072
	s_add_u32 s46, s46, 0x1000
	s_addc_u32 s47, s47, 0
	s_add_u32 s62, s62, 0x800
	s_addc_u32 s63, s63, 0
	s_waitcnt vmcnt(20)
	v_lshlrev_b32_e32 v14, 16, v86
	v_and_b32_e32 v15, 0xffff0000, v86
	v_lshlrev_b32_e32 v16, 16, v88
	v_and_b32_e32 v17, 0xffff0000, v88
	v_lshlrev_b32_e32 v18, 16, v87
	v_and_b32_e32 v19, 0xffff0000, v87
	v_lshlrev_b32_e32 v20, 16, v89
	v_and_b32_e32 v21, 0xffff0000, v89
	v_pk_add_f32 v[86:87], v[14:15], v[16:17]
	v_pk_add_f32 v[88:89], v[18:19], v[20:21]
	v_lshlrev_b32_e32 v14, 16, v90
	v_and_b32_e32 v15, 0xffff0000, v90
	v_lshlrev_b32_e32 v16, 16, v92
	v_and_b32_e32 v17, 0xffff0000, v92
	v_lshlrev_b32_e32 v18, 16, v91
	v_and_b32_e32 v19, 0xffff0000, v91
	v_lshlrev_b32_e32 v20, 16, v93
	v_and_b32_e32 v21, 0xffff0000, v93
	v_pk_add_f32 v[90:91], v[14:15], v[16:17]
	v_pk_add_f32 v[92:93], v[18:19], v[20:21]
	v_lshlrev_b32_e32 v14, 16, v94
	v_and_b32_e32 v15, 0xffff0000, v94
	v_lshlrev_b32_e32 v16, 16, v96
	v_and_b32_e32 v17, 0xffff0000, v96
	v_lshlrev_b32_e32 v18, 16, v95
	v_and_b32_e32 v19, 0xffff0000, v95
	v_lshlrev_b32_e32 v20, 16, v97
	v_and_b32_e32 v21, 0xffff0000, v97
	v_pk_add_f32 v[94:95], v[14:15], v[16:17]
	v_pk_add_f32 v[96:97], v[18:19], v[20:21]
	v_lshlrev_b32_e32 v14, 16, v98
	v_and_b32_e32 v15, 0xffff0000, v98
	v_lshlrev_b32_e32 v16, 16, v100
	v_and_b32_e32 v17, 0xffff0000, v100
	v_lshlrev_b32_e32 v18, 16, v99
	v_and_b32_e32 v19, 0xffff0000, v99
	v_lshlrev_b32_e32 v20, 16, v101
	v_and_b32_e32 v21, 0xffff0000, v101
	v_pk_add_f32 v[98:99], v[14:15], v[16:17]
	v_pk_add_f32 v[100:101], v[18:19], v[20:21]
	v_pk_mul_f32 v[12:13], v[86:87], v[86:87]
	v_pk_fma_f32 v[12:13], v[88:89], v[88:89], v[12:13]
	v_pk_fma_f32 v[12:13], v[90:91], v[90:91], v[12:13]
	v_pk_fma_f32 v[12:13], v[92:93], v[92:93], v[12:13]
	v_pk_fma_f32 v[12:13], v[94:95], v[94:95], v[12:13]
	v_pk_fma_f32 v[12:13], v[96:97], v[96:97], v[12:13]
	v_pk_fma_f32 v[12:13], v[98:99], v[98:99], v[12:13]
	v_pk_fma_f32 v[12:13], v[100:101], v[100:101], v[12:13]
	v_add_f32_e32 v5, v12, v13
	s_nop 1
	v_add_f32_dpp v5, v5, v5 quad_perm:[1,0,3,2] row_mask:0xf bank_mask:0xf
	s_nop 1
	v_add_f32_dpp v5, v5, v5 quad_perm:[2,3,0,1] row_mask:0xf bank_mask:0xf
	s_nop 1
	v_add_f32_dpp v5, v5, v5 row_half_mirror row_mask:0xf bank_mask:0xf
	s_nop 1
	v_add_f32_dpp v5, v5, v5 row_mirror row_mask:0xf bank_mask:0xf
	s_nop 1
	v_add_f32_dpp v5, v5, v5 row_bcast:15 row_mask:0xa bank_mask:0xf
	s_nop 1
	v_add_f32_dpp v5, v5, v5 row_bcast:31 row_mask:0xc bank_mask:0xf
	s_nop 1
	v_readlane_b32 s32, v5, 63
	s_nop 1
	v_mov_b32_e32 v6, s32
	v_fmamk_f32 v6, v6, 0x3a800000, v146
	v_rsq_f32_e32 v6, v6
	s_nop 0
	v_mul_f32_e32 v8, 0.5, v6
	v_pk_mul_f32 v[14:15], v[86:87], v[8:9] op_sel_hi:[1,0]
	v_pk_fma_f32 v[70:71], v[22:23], v[14:15], v[70:71]
	v_pk_mul_f32 v[14:15], v[88:89], v[8:9] op_sel_hi:[1,0]
	v_pk_fma_f32 v[72:73], v[24:25], v[14:15], v[72:73]
	v_pk_mul_f32 v[14:15], v[90:91], v[8:9] op_sel_hi:[1,0]
	v_pk_fma_f32 v[74:75], v[26:27], v[14:15], v[74:75]
	v_pk_mul_f32 v[14:15], v[92:93], v[8:9] op_sel_hi:[1,0]
	v_pk_fma_f32 v[76:77], v[28:29], v[14:15], v[76:77]
	v_pk_mul_f32 v[14:15], v[94:95], v[8:9] op_sel_hi:[1,0]
	v_pk_fma_f32 v[78:79], v[30:31], v[14:15], v[78:79]
	v_pk_mul_f32 v[14:15], v[96:97], v[8:9] op_sel_hi:[1,0]
	v_pk_fma_f32 v[80:81], v[32:33], v[14:15], v[80:81]
	v_pk_mul_f32 v[14:15], v[98:99], v[8:9] op_sel_hi:[1,0]
	v_pk_fma_f32 v[82:83], v[34:35], v[14:15], v[82:83]
	v_pk_mul_f32 v[14:15], v[100:101], v[8:9] op_sel_hi:[1,0]
	v_pk_fma_f32 v[84:85], v[36:37], v[14:15], v[84:85]
	global_store_dwordx4 v0, v[70:73], s[46:47] offset:0
	global_store_dwordx4 v0, v[74:77], s[46:47] offset:1024
	global_store_dwordx4 v0, v[78:81], s[46:47] offset:2048
	global_store_dwordx4 v0, v[82:85], s[46:47] offset:3072
	s_add_u32 s46, s46, 0x1000
	s_addc_u32 s47, s47, 0
	s_add_u32 s62, s62, 0x800
	s_addc_u32 s63, s63, 0
	s_waitcnt vmcnt(16)
	v_lshlrev_b32_e32 v14, 16, v118
	v_and_b32_e32 v15, 0xffff0000, v118
	v_lshlrev_b32_e32 v16, 16, v120
	v_and_b32_e32 v17, 0xffff0000, v120
	v_lshlrev_b32_e32 v18, 16, v119
	v_and_b32_e32 v19, 0xffff0000, v119
	v_lshlrev_b32_e32 v20, 16, v121
	v_and_b32_e32 v21, 0xffff0000, v121
	v_pk_add_f32 v[118:119], v[14:15], v[16:17]
	v_pk_add_f32 v[120:121], v[18:19], v[20:21]
	v_lshlrev_b32_e32 v14, 16, v122
	v_and_b32_e32 v15, 0xffff0000, v122
	v_lshlrev_b32_e32 v16, 16, v124
	v_and_b32_e32 v17, 0xffff0000, v124
	v_lshlrev_b32_e32 v18, 16, v123
	v_and_b32_e32 v19, 0xffff0000, v123
	v_lshlrev_b32_e32 v20, 16, v125
	v_and_b32_e32 v21, 0xffff0000, v125
	v_pk_add_f32 v[122:123], v[14:15], v[16:17]
	v_pk_add_f32 v[124:125], v[18:19], v[20:21]
	v_lshlrev_b32_e32 v14, 16, v134
	v_and_b32_e32 v15, 0xffff0000, v134
	v_lshlrev_b32_e32 v16, 16, v136
	v_and_b32_e32 v17, 0xffff0000, v136
	v_lshlrev_b32_e32 v18, 16, v135
	v_and_b32_e32 v19, 0xffff0000, v135
	v_lshlrev_b32_e32 v20, 16, v137
	v_and_b32_e32 v21, 0xffff0000, v137
	v_pk_add_f32 v[134:135], v[14:15], v[16:17]
	v_pk_add_f32 v[136:137], v[18:19], v[20:21]
	v_lshlrev_b32_e32 v14, 16, v138
	v_and_b32_e32 v15, 0xffff0000, v138
	v_lshlrev_b32_e32 v16, 16, v140
	v_and_b32_e32 v17, 0xffff0000, v140
	v_lshlrev_b32_e32 v18, 16, v139
	v_and_b32_e32 v19, 0xffff0000, v139
	v_lshlrev_b32_e32 v20, 16, v141
	v_and_b32_e32 v21, 0xffff0000, v141
	v_pk_add_f32 v[138:139], v[14:15], v[16:17]
	v_pk_add_f32 v[140:141], v[18:19], v[20:21]
	v_pk_mul_f32 v[12:13], v[118:119], v[118:119]
	v_pk_fma_f32 v[12:13], v[120:121], v[120:121], v[12:13]
	v_pk_fma_f32 v[12:13], v[122:123], v[122:123], v[12:13]
	v_pk_fma_f32 v[12:13], v[124:125], v[124:125], v[12:13]
	v_pk_fma_f32 v[12:13], v[134:135], v[134:135], v[12:13]
	v_pk_fma_f32 v[12:13], v[136:137], v[136:137], v[12:13]
	v_pk_fma_f32 v[12:13], v[138:139], v[138:139], v[12:13]
	v_pk_fma_f32 v[12:13], v[140:141], v[140:141], v[12:13]
	v_add_f32_e32 v5, v12, v13
	s_nop 1
	v_add_f32_dpp v5, v5, v5 quad_perm:[1,0,3,2] row_mask:0xf bank_mask:0xf
	s_nop 1
	v_add_f32_dpp v5, v5, v5 quad_perm:[2,3,0,1] row_mask:0xf bank_mask:0xf
	s_nop 1
	v_add_f32_dpp v5, v5, v5 row_half_mirror row_mask:0xf bank_mask:0xf
	s_nop 1
	v_add_f32_dpp v5, v5, v5 row_mirror row_mask:0xf bank_mask:0xf
	s_nop 1
	v_add_f32_dpp v5, v5, v5 row_bcast:15 row_mask:0xa bank_mask:0xf
	s_nop 1
	v_add_f32_dpp v5, v5, v5 row_bcast:31 row_mask:0xc bank_mask:0xf
	s_nop 1
	v_readlane_b32 s32, v5, 63
	s_nop 1
	v_mov_b32_e32 v6, s32
	v_fmamk_f32 v6, v6, 0x3a800000, v146
	v_rsq_f32_e32 v6, v6
	s_nop 0
	v_mul_f32_e32 v8, 0.5, v6
	v_pk_mul_f32 v[14:15], v[118:119], v[8:9] op_sel_hi:[1,0]
	v_pk_fma_f32 v[102:103], v[22:23], v[14:15], v[102:103]
	v_pk_mul_f32 v[14:15], v[120:121], v[8:9] op_sel_hi:[1,0]
	v_pk_fma_f32 v[104:105], v[24:25], v[14:15], v[104:105]
	v_pk_mul_f32 v[14:15], v[122:123], v[8:9] op_sel_hi:[1,0]
	v_pk_fma_f32 v[106:107], v[26:27], v[14:15], v[106:107]
	v_pk_mul_f32 v[14:15], v[124:125], v[8:9] op_sel_hi:[1,0]
	v_pk_fma_f32 v[108:109], v[28:29], v[14:15], v[108:109]
	v_pk_mul_f32 v[14:15], v[134:135], v[8:9] op_sel_hi:[1,0]
	v_pk_fma_f32 v[110:111], v[30:31], v[14:15], v[110:111]
	v_pk_mul_f32 v[14:15], v[136:137], v[8:9] op_sel_hi:[1,0]
	v_pk_fma_f32 v[112:113], v[32:33], v[14:15], v[112:113]
	v_pk_mul_f32 v[14:15], v[138:139], v[8:9] op_sel_hi:[1,0]
	v_pk_fma_f32 v[114:115], v[34:35], v[14:15], v[114:115]
	v_pk_mul_f32 v[14:15], v[140:141], v[8:9] op_sel_hi:[1,0]
	v_pk_fma_f32 v[116:117], v[36:37], v[14:15], v[116:117]
	global_store_dwordx4 v0, v[102:105], s[46:47] offset:0
	global_store_dwordx4 v0, v[106:109], s[46:47] offset:1024
	global_store_dwordx4 v0, v[110:113], s[46:47] offset:2048
	global_store_dwordx4 v0, v[114:117], s[46:47] offset:3072
	s_add_u32 s46, s46, 0x1000
	s_addc_u32 s47, s47, 0
	s_add_u32 s62, s62, 0x800
	s_addc_u32 s63, s63, 0
	s_waitcnt vmcnt(12)
	v_lshlrev_b32_e32 v14, 16, v172
	v_and_b32_e32 v15, 0xffff0000, v172
	v_lshlrev_b32_e32 v16, 16, v174
	v_and_b32_e32 v17, 0xffff0000, v174
	v_lshlrev_b32_e32 v18, 16, v173
	v_and_b32_e32 v19, 0xffff0000, v173
	v_lshlrev_b32_e32 v20, 16, v175
	v_and_b32_e32 v21, 0xffff0000, v175
	v_pk_add_f32 v[172:173], v[14:15], v[16:17]
	v_pk_add_f32 v[174:175], v[18:19], v[20:21]
	v_lshlrev_b32_e32 v14, 16, v176
	v_and_b32_e32 v15, 0xffff0000, v176
	v_lshlrev_b32_e32 v16, 16, v178
	v_and_b32_e32 v17, 0xffff0000, v178
	v_lshlrev_b32_e32 v18, 16, v177
	v_and_b32_e32 v19, 0xffff0000, v177
	v_lshlrev_b32_e32 v20, 16, v179
	v_and_b32_e32 v21, 0xffff0000, v179
	v_pk_add_f32 v[176:177], v[14:15], v[16:17]
	v_pk_add_f32 v[178:179], v[18:19], v[20:21]
	v_lshlrev_b32_e32 v14, 16, v204
	v_and_b32_e32 v15, 0xffff0000, v204
	v_lshlrev_b32_e32 v16, 16, v206
	v_and_b32_e32 v17, 0xffff0000, v206
	v_lshlrev_b32_e32 v18, 16, v205
	v_and_b32_e32 v19, 0xffff0000, v205
	v_lshlrev_b32_e32 v20, 16, v207
	v_and_b32_e32 v21, 0xffff0000, v207
	v_pk_add_f32 v[204:205], v[14:15], v[16:17]
	v_pk_add_f32 v[206:207], v[18:19], v[20:21]
	v_lshlrev_b32_e32 v14, 16, v214
	v_and_b32_e32 v15, 0xffff0000, v214
	v_lshlrev_b32_e32 v16, 16, v216
	v_and_b32_e32 v17, 0xffff0000, v216
	v_lshlrev_b32_e32 v18, 16, v215
	v_and_b32_e32 v19, 0xffff0000, v215
	v_lshlrev_b32_e32 v20, 16, v217
	v_and_b32_e32 v21, 0xffff0000, v217
	v_pk_add_f32 v[214:215], v[14:15], v[16:17]
	v_pk_add_f32 v[216:217], v[18:19], v[20:21]
	v_pk_mul_f32 v[12:13], v[172:173], v[172:173]
	v_pk_fma_f32 v[12:13], v[174:175], v[174:175], v[12:13]
	v_pk_fma_f32 v[12:13], v[176:177], v[176:177], v[12:13]
	v_pk_fma_f32 v[12:13], v[178:179], v[178:179], v[12:13]
	v_pk_fma_f32 v[12:13], v[204:205], v[204:205], v[12:13]
	v_pk_fma_f32 v[12:13], v[206:207], v[206:207], v[12:13]
	v_pk_fma_f32 v[12:13], v[214:215], v[214:215], v[12:13]
	v_pk_fma_f32 v[12:13], v[216:217], v[216:217], v[12:13]
	v_add_f32_e32 v5, v12, v13
	s_nop 1
	v_add_f32_dpp v5, v5, v5 quad_perm:[1,0,3,2] row_mask:0xf bank_mask:0xf
	s_nop 1
	v_add_f32_dpp v5, v5, v5 quad_perm:[2,3,0,1] row_mask:0xf bank_mask:0xf
	s_nop 1
	v_add_f32_dpp v5, v5, v5 row_half_mirror row_mask:0xf bank_mask:0xf
	s_nop 1
	v_add_f32_dpp v5, v5, v5 row_mirror row_mask:0xf bank_mask:0xf
	s_nop 1
	v_add_f32_dpp v5, v5, v5 row_bcast:15 row_mask:0xa bank_mask:0xf
	s_nop 1
	v_add_f32_dpp v5, v5, v5 row_bcast:31 row_mask:0xc bank_mask:0xf
	s_nop 1
	v_readlane_b32 s32, v5, 63
	s_nop 1
	v_mov_b32_e32 v6, s32
	v_fmamk_f32 v6, v6, 0x3a800000, v146
	v_rsq_f32_e32 v6, v6
	s_nop 0
	v_mul_f32_e32 v8, 0.5, v6
	v_pk_mul_f32 v[14:15], v[172:173], v[8:9] op_sel_hi:[1,0]
	v_pk_fma_f32 v[154:155], v[22:23], v[14:15], v[154:155]
	v_pk_mul_f32 v[14:15], v[174:175], v[8:9] op_sel_hi:[1,0]
	v_pk_fma_f32 v[156:157], v[24:25], v[14:15], v[156:157]
	v_pk_mul_f32 v[14:15], v[176:177], v[8:9] op_sel_hi:[1,0]
	v_pk_fma_f32 v[158:159], v[26:27], v[14:15], v[158:159]
	v_pk_mul_f32 v[14:15], v[178:179], v[8:9] op_sel_hi:[1,0]
	v_pk_fma_f32 v[160:161], v[28:29], v[14:15], v[160:161]
	v_pk_mul_f32 v[14:15], v[204:205], v[8:9] op_sel_hi:[1,0]
	v_pk_fma_f32 v[162:163], v[30:31], v[14:15], v[162:163]
	v_pk_mul_f32 v[14:15], v[206:207], v[8:9] op_sel_hi:[1,0]
	v_pk_fma_f32 v[164:165], v[32:33], v[14:15], v[164:165]
	v_pk_mul_f32 v[14:15], v[214:215], v[8:9] op_sel_hi:[1,0]
	v_pk_fma_f32 v[168:169], v[34:35], v[14:15], v[168:169]
	v_pk_mul_f32 v[14:15], v[216:217], v[8:9] op_sel_hi:[1,0]
	v_pk_fma_f32 v[170:171], v[36:37], v[14:15], v[170:171]
	global_store_dwordx4 v0, v[154:157], s[46:47] offset:0
	global_store_dwordx4 v0, v[158:161], s[46:47] offset:1024
	global_store_dwordx4 v0, v[162:165], s[46:47] offset:2048
	global_store_dwordx4 v0, v[168:171], s[46:47] offset:3072
	s_add_u32 s46, s46, 0x1000
	s_addc_u32 s47, s47, 0
	s_add_u32 s62, s62, 0x800
	s_addc_u32 s63, s63, 0
